# same two edits as v36, padded/reordered so every downstream code address equals v29 (size-neutral edits)
# speedup vs baseline: 1.0028x; 1.0028x over previous
; #define PG8_STAGE(bufoff, gbase) do { _Pragma("unroll") for (int _i = 0; _i < 2; ++_i) \
;         __builtin_amdgcn_global_load_lds((const unsigned*)((const char*)(gbase) + voff[_i]), (LAS unsigned*)(lds + (bufoff) + ldsw + _i * 8192), 16, 0, 0); } while (0)
; #define PG8_LDA(dst, b, h) do { _Pragma("unroll") for (int m = 0; m < 4; ++m) _Pragma("unroll") for (int k = 0; k < 2; ++k) dst[m][k] = *(const LAS bf16x8*)(lds + PG8_SA(b, h) + aoff + m * 2048 + k * 1024); } while (0)
; #define PG8_LDB(dst, b, h) do { _Pragma("unroll") for (int n = 0; n < 2; ++n) _Pragma("unroll") for (int k = 0; k < 2; ++k) dst[n][k] = *(const LAS bf16x8*)(lds + PG8_SB(b, h) + boff + n * 2048 + k * 1024); } while (0)
; #define PG8_WAIT_V(n) asm volatile("s_waitcnt vmcnt(" #n ")" ::: "memory")
; #define PG8_WAIT_L(n) asm volatile("s_waitcnt lgkmcnt(" #n ")" ::: "memory")
; #define PG8_BAR __builtin_amdgcn_s_barrier()
; #define PG8_SCHED __builtin_amdgcn_sched_barrier(0)
;     ...
;             PG8_LDB(B0, 0, 0); PG8_SCHED; PG8_LDA(At, 0, 0); PG8_STAGE(PG8_SA(1, 1), a1 + hstep);
;             PG8_WAIT_L(8); PG8_BAR; PG8_WAIT_L(0); PG8_MMA(0, 0, At, B0); PG8_BAR; PG8_SCHED;
;             PG8_LDB(B1, 0, 1); PG8_STAGE(PG8_SB(0, 0), b2);
;             PG8_BAR; PG8_WAIT_L(0); PG8_MMA(0, 1, At, B1); PG8_BAR;
;             PG8_LDA(At, 0, 1); PG8_STAGE(PG8_SA(0, 0), a2);
;             PG8_BAR; PG8_WAIT_L(0); PG8_MMA(1, 0, At, B0); PG8_BAR; PG8_SCHED;
;             PG8_STAGE(PG8_SB(0, 1), b2 + hstep);
;             PG8_WAIT_V(6); PG8_BAR; PG8_MMA(1, 1, At, B1); PG8_BAR;
.LBB0_161:
	s_add_u32 s0, s10, 0xfffc0080
	s_addc_u32 s1, s11, -1
	s_add_i32 s29, 0, 0x10000
	v_add_u32_e32 v162, s29, v1
	ds_read_b128 v[158:161], v162
	ds_read_b128 v[168:171], v162 offset:1024
	ds_read_b128 v[172:175], v162 offset:2048
	ds_read_b128 v[194:197], v162 offset:3072
	s_cmp_eq_u32 s28, 12
	s_cselect_b32 s15, s4, s1
	s_cselect_b32 s14, s7, s0
	s_cselect_b32 s13, s18, s23
	s_cselect_b32 s12, s19, s22
	v_lshl_add_u64 v[162:163], s[10:11], 0, v[154:155]
	s_add_i32 m0, s17, 0xc000
	ds_read_b128 v[198:201], v166
	ds_read_b128 v[202:205], v166 offset:1024
	ds_read_b128 v[206:209], v166 offset:2048
	ds_read_b128 v[210:213], v166 offset:3072
	ds_read_b128 v[214:217], v166 offset:4096
	ds_read_b128 v[218:221], v166 offset:5120
	ds_read_b128 v[222:225], v166 offset:6144
	ds_read_b128 v[226:229], v166 offset:7168
	global_load_lds_dwordx4 v[162:163], off
	s_add_i32 m0, s17, 0xe000
	v_lshl_add_u64 v[162:163], s[10:11], 0, v[156:157]
	global_load_lds_dwordx4 v[162:163], off
	s_waitcnt lgkmcnt(8)
	s_barrier
	s_waitcnt lgkmcnt(0)
	s_setprio 1
	v_mfma_f32_16x16x32_bf16 v[126:129], v[198:201], v[158:161], v[126:129]
	v_mfma_f32_16x16x32_bf16 v[110:113], v[198:201], v[172:175], v[110:113]
	v_mfma_f32_16x16x32_bf16 v[122:125], v[206:209], v[158:161], v[122:125]
	v_mfma_f32_16x16x32_bf16 v[106:109], v[206:209], v[172:175], v[106:109]
	v_mfma_f32_16x16x32_bf16 v[118:121], v[214:217], v[158:161], v[118:121]
	v_mfma_f32_16x16x32_bf16 v[102:105], v[214:217], v[172:175], v[102:105]
	v_mfma_f32_16x16x32_bf16 v[114:117], v[222:225], v[158:161], v[114:117]
	v_mfma_f32_16x16x32_bf16 v[94:97], v[222:225], v[172:175], v[94:97]
	v_mfma_f32_16x16x32_bf16 v[126:129], v[202:205], v[168:171], v[126:129]
	v_mfma_f32_16x16x32_bf16 v[110:113], v[202:205], v[194:197], v[110:113]
	v_mfma_f32_16x16x32_bf16 v[122:125], v[210:213], v[168:171], v[122:125]
	v_mfma_f32_16x16x32_bf16 v[106:109], v[210:213], v[194:197], v[106:109]
	v_mfma_f32_16x16x32_bf16 v[118:121], v[218:221], v[168:171], v[118:121]
	v_mfma_f32_16x16x32_bf16 v[102:105], v[218:221], v[194:197], v[102:105]
	v_mfma_f32_16x16x32_bf16 v[114:117], v[226:229], v[168:171], v[114:117]
	v_mfma_f32_16x16x32_bf16 v[94:97], v[226:229], v[194:197], v[94:97]
	s_setprio 0
	s_barrier
	s_add_i32 s0, 0, 0x14000
	v_add_u32_e32 v162, s0, v1
	s_add_i32 s1, s29, s16
	ds_read_b128 v[230:233], v162
	ds_read_b128 v[234:237], v162 offset:1024
	ds_read_b128 v[238:241], v162 offset:2048
	ds_read_b128 v[242:245], v162 offset:3072
	v_lshl_add_u64 v[162:163], s[12:13], 0, v[132:133]
	s_mov_b32 m0, s1
	v_lshl_add_u64 v[246:247], s[12:13], 0, v[130:131]
	global_load_lds_dwordx4 v[162:163], off
	s_add_i32 m0, s1, 0x2000
	s_nop 0
	global_load_lds_dwordx4 v[246:247], off
	s_barrier
	s_waitcnt lgkmcnt(0)
	s_setprio 1
	v_mfma_f32_16x16x32_bf16 v[82:85], v[198:201], v[230:233], v[82:85]
	v_mfma_f32_16x16x32_bf16 v[50:53], v[198:201], v[238:241], v[50:53]
	v_mfma_f32_16x16x32_bf16 v[74:77], v[206:209], v[230:233], v[74:77]
	v_mfma_f32_16x16x32_bf16 v[42:45], v[206:209], v[238:241], v[42:45]
	v_mfma_f32_16x16x32_bf16 v[66:69], v[214:217], v[230:233], v[66:69]
	v_mfma_f32_16x16x32_bf16 v[38:41], v[214:217], v[238:241], v[38:41]
	v_mfma_f32_16x16x32_bf16 v[58:61], v[222:225], v[230:233], v[58:61]
	v_mfma_f32_16x16x32_bf16 v[30:33], v[222:225], v[238:241], v[30:33]
	v_mfma_f32_16x16x32_bf16 v[82:85], v[202:205], v[234:237], v[82:85]
	v_mfma_f32_16x16x32_bf16 v[50:53], v[202:205], v[242:245], v[50:53]
	v_mfma_f32_16x16x32_bf16 v[74:77], v[210:213], v[234:237], v[74:77]
	v_mfma_f32_16x16x32_bf16 v[42:45], v[210:213], v[242:245], v[42:45]
	v_mfma_f32_16x16x32_bf16 v[66:69], v[218:221], v[234:237], v[66:69]
	v_mfma_f32_16x16x32_bf16 v[38:41], v[218:221], v[242:245], v[38:41]
	v_mfma_f32_16x16x32_bf16 v[58:61], v[226:229], v[234:237], v[58:61]
	v_mfma_f32_16x16x32_bf16 v[30:33], v[226:229], v[242:245], v[30:33]
	s_setprio 0
	s_mov_b32 m0, s17
	v_lshl_add_u64 v[248:249], s[14:15], 0, v[132:133]
	s_barrier
	ds_read_b128 v[198:201], v166 offset:16384
	ds_read_b128 v[202:205], v166 offset:17408
	ds_read_b128 v[206:209], v166 offset:18432
	ds_read_b128 v[210:213], v166 offset:19456
	ds_read_b128 v[214:217], v166 offset:20480
	ds_read_b128 v[218:221], v166 offset:21504
	ds_read_b128 v[222:225], v166 offset:22528
	ds_read_b128 v[226:229], v166 offset:23552
	global_load_lds_dwordx4 v[248:249], off
	s_mov_b32 m0, s20
	v_lshl_add_u64 v[192:193], s[14:15], 0, v[130:131]
	global_load_lds_dwordx4 v[192:193], off
	s_barrier
	s_waitcnt lgkmcnt(0)
	s_setprio 1
	v_mfma_f32_16x16x32_bf16 v[98:101], v[198:201], v[158:161], v[98:101]
	v_mfma_f32_16x16x32_bf16 v[70:73], v[198:201], v[172:175], v[70:73]
	v_mfma_f32_16x16x32_bf16 v[90:93], v[206:209], v[158:161], v[90:93]
	v_mfma_f32_16x16x32_bf16 v[62:65], v[206:209], v[172:175], v[62:65]
	v_mfma_f32_16x16x32_bf16 v[86:89], v[214:217], v[158:161], v[86:89]
	v_mfma_f32_16x16x32_bf16 v[54:57], v[214:217], v[172:175], v[54:57]
	v_mfma_f32_16x16x32_bf16 v[78:81], v[222:225], v[158:161], v[78:81]
	v_mfma_f32_16x16x32_bf16 v[46:49], v[222:225], v[172:175], v[46:49]
	v_mfma_f32_16x16x32_bf16 v[98:101], v[202:205], v[168:171], v[98:101]
	v_mfma_f32_16x16x32_bf16 v[70:73], v[202:205], v[194:197], v[70:73]
	v_mfma_f32_16x16x32_bf16 v[90:93], v[210:213], v[168:171], v[90:93]
	v_mfma_f32_16x16x32_bf16 v[62:65], v[210:213], v[194:197], v[62:65]
	v_mfma_f32_16x16x32_bf16 v[86:89], v[218:221], v[168:171], v[86:89]
	v_mfma_f32_16x16x32_bf16 v[54:57], v[218:221], v[194:197], v[54:57]
	v_mfma_f32_16x16x32_bf16 v[78:81], v[226:229], v[168:171], v[78:81]
	v_mfma_f32_16x16x32_bf16 v[46:49], v[226:229], v[194:197], v[46:49]
	s_setprio 0
	s_barrier
; #define PG8_STAGE(bufoff, gbase) do { _Pragma("unroll") for (int _i = 0; _i < 2; ++_i) \
;         __builtin_amdgcn_global_load_lds((const unsigned*)((const char*)(gbase) + voff[_i]), (LAS unsigned*)(lds + (bufoff) + ldsw + _i * 8192), 16, 0, 0); } while (0)
; #define PG8_LDA(dst, b, h) do { _Pragma("unroll") for (int m = 0; m < 4; ++m) _Pragma("unroll") for (int k = 0; k < 2; ++k) dst[m][k] = *(const LAS bf16x8*)(lds + PG8_SA(b, h) + aoff + m * 2048 + k * 1024); } while (0)
; #define PG8_LDB(dst, b, h) do { _Pragma("unroll") for (int n = 0; n < 2; ++n) _Pragma("unroll") for (int k = 0; k < 2; ++k) dst[n][k] = *(const LAS bf16x8*)(lds + PG8_SB(b, h) + boff + n * 2048 + k * 1024); } while (0)
; #define PG8_WAIT_V(n) asm volatile("s_waitcnt vmcnt(" #n ")" ::: "memory")
; #define PG8_WAIT_L(n) asm volatile("s_waitcnt lgkmcnt(" #n ")" ::: "memory")
; #define PG8_BAR __builtin_amdgcn_s_barrier()
; #define PG8_SCHED __builtin_amdgcn_sched_barrier(0)
;     ...
;             PG8_STAGE(PG8_SB(0, 1), b2 + hstep);
;             PG8_WAIT_V(6); PG8_BAR; PG8_MMA(1, 1, At, B1); PG8_BAR;
;             PG8_LDB(B0, 1, 0); PG8_SCHED; PG8_LDA(At, 1, 0); PG8_STAGE(PG8_SA(0, 1), a2 + hstep);
;             PG8_WAIT_L(8); PG8_BAR; PG8_WAIT_L(0); PG8_MMA(0, 0, At, B0); PG8_BAR; PG8_SCHED;
;             PG8_LDB(B1, 1, 1); PG8_STAGE(PG8_SB(1, 0), b3);
;             PG8_BAR; PG8_WAIT_L(0); PG8_MMA(0, 1, At, B1); PG8_BAR;
;             PG8_LDA(At, 1, 1); PG8_STAGE(PG8_SA(1, 0), a3);
;             PG8_BAR; PG8_WAIT_L(0); PG8_MMA(1, 0, At, B0); PG8_BAR; PG8_SCHED;
	s_add_u32 s30, s12, 0x40000
	s_addc_u32 s31, s13, 0
	s_add_i32 s0, s0, s16
	s_mov_b32 m0, s0
	v_lshl_add_u64 v[158:159], s[30:31], 0, v[132:133]
	global_load_lds_dwordx4 v[158:159], off
	s_add_i32 m0, s0, 0x2000
	v_lshl_add_u64 v[158:159], s[30:31], 0, v[130:131]
	global_load_lds_dwordx4 v[158:159], off
	s_waitcnt vmcnt(6)
	s_barrier
	s_setprio 1
	v_mfma_f32_16x16x32_bf16 v[34:37], v[198:201], v[230:233], v[34:37]
	v_mfma_f32_16x16x32_bf16 v[14:17], v[198:201], v[238:241], v[14:17]
	v_mfma_f32_16x16x32_bf16 v[26:29], v[206:209], v[230:233], v[26:29]
	v_mfma_f32_16x16x32_bf16 v[10:13], v[206:209], v[238:241], v[10:13]
	v_mfma_f32_16x16x32_bf16 v[22:25], v[214:217], v[230:233], v[22:25]
	v_mfma_f32_16x16x32_bf16 v[6:9], v[214:217], v[238:241], v[6:9]
	v_mfma_f32_16x16x32_bf16 v[18:21], v[222:225], v[230:233], v[18:21]
	v_mfma_f32_16x16x32_bf16 v[2:5], v[222:225], v[238:241], v[2:5]
	v_mfma_f32_16x16x32_bf16 v[34:37], v[202:205], v[234:237], v[34:37]
	v_mfma_f32_16x16x32_bf16 v[14:17], v[202:205], v[242:245], v[14:17]
	v_mfma_f32_16x16x32_bf16 v[26:29], v[210:213], v[234:237], v[26:29]
	v_mfma_f32_16x16x32_bf16 v[10:13], v[210:213], v[242:245], v[10:13]
	v_mfma_f32_16x16x32_bf16 v[22:25], v[218:221], v[234:237], v[22:25]
	v_mfma_f32_16x16x32_bf16 v[6:9], v[218:221], v[242:245], v[6:9]
	v_mfma_f32_16x16x32_bf16 v[18:21], v[226:229], v[234:237], v[18:21]
	v_mfma_f32_16x16x32_bf16 v[2:5], v[226:229], v[242:245], v[2:5]
	s_setprio 0
	s_add_i32 s0, 0, 0x18000
	v_add_u32_e32 v194, s0, v1
	s_barrier
	ds_read_b128 v[158:161], v194
	ds_read_b128 v[168:171], v194 offset:1024
	ds_read_b128 v[172:175], v194 offset:2048
	ds_read_b128 v[194:197], v194 offset:3072
	s_add_u32 s14, s14, 0x40000
	s_addc_u32 s15, s15, 0
	s_mov_b32 m0, s40
	v_lshl_add_u64 v[230:231], s[14:15], 0, v[132:133]
	ds_read_b128 v[198:201], v166 offset:32768
	ds_read_b128 v[202:205], v166 offset:33792
	ds_read_b128 v[206:209], v166 offset:34816
	ds_read_b128 v[210:213], v166 offset:35840
	ds_read_b128 v[214:217], v166 offset:36864
	ds_read_b128 v[218:221], v166 offset:37888
	ds_read_b128 v[222:225], v166 offset:38912
	ds_read_b128 v[226:229], v166 offset:39936
	global_load_lds_dwordx4 v[230:231], off
	s_mov_b32 m0, s41
	v_lshl_add_u64 v[230:231], s[14:15], 0, v[130:131]
	global_load_lds_dwordx4 v[230:231], off
	s_waitcnt lgkmcnt(8)
	s_barrier
	s_waitcnt lgkmcnt(0)
	s_setprio 1
	v_mfma_f32_16x16x32_bf16 v[126:129], v[198:201], v[158:161], v[126:129]
	v_mfma_f32_16x16x32_bf16 v[110:113], v[198:201], v[172:175], v[110:113]
	v_mfma_f32_16x16x32_bf16 v[122:125], v[206:209], v[158:161], v[122:125]
	v_mfma_f32_16x16x32_bf16 v[106:109], v[206:209], v[172:175], v[106:109]
	v_mfma_f32_16x16x32_bf16 v[118:121], v[214:217], v[158:161], v[118:121]
	v_mfma_f32_16x16x32_bf16 v[102:105], v[214:217], v[172:175], v[102:105]
	v_mfma_f32_16x16x32_bf16 v[114:117], v[222:225], v[158:161], v[114:117]
	v_mfma_f32_16x16x32_bf16 v[94:97], v[222:225], v[172:175], v[94:97]
	v_mfma_f32_16x16x32_bf16 v[126:129], v[202:205], v[168:171], v[126:129]
	v_mfma_f32_16x16x32_bf16 v[110:113], v[202:205], v[194:197], v[110:113]
	v_mfma_f32_16x16x32_bf16 v[122:125], v[210:213], v[168:171], v[122:125]
	v_mfma_f32_16x16x32_bf16 v[106:109], v[210:213], v[194:197], v[106:109]
	v_mfma_f32_16x16x32_bf16 v[118:121], v[218:221], v[168:171], v[118:121]
	v_mfma_f32_16x16x32_bf16 v[102:105], v[218:221], v[194:197], v[102:105]
	v_mfma_f32_16x16x32_bf16 v[114:117], v[226:229], v[168:171], v[114:117]
	v_mfma_f32_16x16x32_bf16 v[94:97], v[226:229], v[194:197], v[94:97]
	s_setprio 0
	s_barrier
	s_add_i32 s1, 0, 0x1c000
	s_add_i32 s0, s0, s16
	v_add_u32_e32 v242, s1, v1
	v_lshl_add_u64 v[162:163], v[162:163], 0, s[88:89]
	s_mov_b32 m0, s0
	ds_read_b128 v[230:233], v242
	ds_read_b128 v[234:237], v242 offset:1024
	ds_read_b128 v[238:241], v242 offset:2048
	ds_read_b128 v[242:245], v242 offset:3072
	global_load_lds_dwordx4 v[162:163], off
	s_add_i32 m0, s0, 0x2000
	v_lshl_add_u64 v[162:163], v[246:247], 0, s[88:89]
	global_load_lds_dwordx4 v[162:163], off
	s_barrier
	s_waitcnt lgkmcnt(0)
	s_setprio 1
	v_mfma_f32_16x16x32_bf16 v[82:85], v[198:201], v[230:233], v[82:85]
	v_mfma_f32_16x16x32_bf16 v[50:53], v[198:201], v[238:241], v[50:53]
	v_mfma_f32_16x16x32_bf16 v[74:77], v[206:209], v[230:233], v[74:77]
	v_mfma_f32_16x16x32_bf16 v[42:45], v[206:209], v[238:241], v[42:45]
	v_mfma_f32_16x16x32_bf16 v[66:69], v[214:217], v[230:233], v[66:69]
	v_mfma_f32_16x16x32_bf16 v[38:41], v[214:217], v[238:241], v[38:41]
	v_mfma_f32_16x16x32_bf16 v[58:61], v[222:225], v[230:233], v[58:61]
	v_mfma_f32_16x16x32_bf16 v[30:33], v[222:225], v[238:241], v[30:33]
	v_mfma_f32_16x16x32_bf16 v[82:85], v[202:205], v[234:237], v[82:85]
	v_mfma_f32_16x16x32_bf16 v[50:53], v[202:205], v[242:245], v[50:53]
	v_mfma_f32_16x16x32_bf16 v[74:77], v[210:213], v[234:237], v[74:77]
	v_mfma_f32_16x16x32_bf16 v[42:45], v[210:213], v[242:245], v[42:45]
	v_mfma_f32_16x16x32_bf16 v[66:69], v[218:221], v[234:237], v[66:69]
	v_mfma_f32_16x16x32_bf16 v[38:41], v[218:221], v[242:245], v[38:41]
	v_mfma_f32_16x16x32_bf16 v[58:61], v[226:229], v[234:237], v[58:61]
	v_mfma_f32_16x16x32_bf16 v[30:33], v[226:229], v[242:245], v[30:33]
	s_setprio 0
	s_mov_b32 m0, s58
	v_lshl_add_u64 v[162:163], v[248:249], 0, s[88:89]
	s_barrier
	ds_read_b128 v[198:201], v166 offset:49152
	ds_read_b128 v[202:205], v166 offset:50176
	ds_read_b128 v[206:209], v166 offset:51200
	ds_read_b128 v[210:213], v166 offset:52224
	ds_read_b128 v[214:217], v166 offset:53248
	ds_read_b128 v[218:221], v166 offset:54272
	ds_read_b128 v[222:225], v166 offset:55296
	ds_read_b128 v[226:229], v166 offset:56320
	global_load_lds_dwordx4 v[162:163], off
	s_mov_b32 m0, s59
	v_lshl_add_u64 v[162:163], v[192:193], 0, s[88:89]
	global_load_lds_dwordx4 v[162:163], off
	s_barrier
; #define PG8_STAGE(bufoff, gbase) do { _Pragma("unroll") for (int _i = 0; _i < 2; ++_i) \
;         __builtin_amdgcn_global_load_lds((const unsigned*)((const char*)(gbase) + voff[_i]), (LAS unsigned*)(lds + (bufoff) + ldsw + _i * 8192), 16, 0, 0); } while (0)
; #define PG8_WAIT_V(n) asm volatile("s_waitcnt vmcnt(" #n ")" ::: "memory")
; #define PG8_WAIT_L(n) asm volatile("s_waitcnt lgkmcnt(" #n ")" ::: "memory")
; #define PG8_BAR __builtin_amdgcn_s_barrier()
; #define PG8_SCHED __builtin_amdgcn_sched_barrier(0)
;     ...
;             PG8_BAR; PG8_WAIT_L(0); PG8_MMA(1, 0, At, B0); PG8_BAR; PG8_SCHED;
;             PG8_STAGE(PG8_SB(1, 1), b3 + hstep);
;             PG8_WAIT_V(6); PG8_BAR; PG8_MMA(1, 1, At, B1); PG8_BAR;
;     __device__ __forceinline__ void operator()(Acc& acc, int pm, int pn, int wr, int wc, int fr, int fq) const {
;         if (pn >= 8) { store_vT(acc, vT, (pn - 8) * 256, pm, wr, wc, fr, fq); return; }
;         const int head = pn * 4 + wc;
;         const bool isk = head >= 16;
;         const float* g = isk ? kg : qg;
;         const float sc = isk ? 1.0f : 0.125f;
;         float gv[2][2];
; #pragma unroll
;         for (int bj = 0; bj < 2; ++bj)
; #pragma unroll
;             for (int n = 0; n < 2; ++n) gv[bj][n] = g[bj * 32 + n * 16 + fr] * sc;
; #pragma unroll
;         for (int ai = 0; ai < 2; ++ai)
; #pragma unroll
;             for (int m = 0; m < 4; ++m)
; #pragma unroll
;                 for (int j = 0; j < 4; ++j) {
;                     float ss = acc[ai][0][m][0][j] * acc[ai][0][m][0][j] + acc[ai][0][m][1][j] * acc[ai][0][m][1][j] +
;                                acc[ai][1][m][0][j] * acc[ai][1][m][0][j] + acc[ai][1][m][1][j] * acc[ai][1][m][1][j];
;                     ss += __shfl_xor(ss, 1); ss += __shfl_xor(ss, 2); ss += __shfl_xor(ss, 4); ss += __shfl_xor(ss, 8);
;                     const float rs = rsqrtf(ss * (1.0f / 64.0f) + EPSV);
	s_waitcnt lgkmcnt(0)
	s_setprio 1
	v_mfma_f32_16x16x32_bf16 v[98:101], v[198:201], v[158:161], v[98:101]
	v_mfma_f32_16x16x32_bf16 v[70:73], v[198:201], v[172:175], v[70:73]
	v_mfma_f32_16x16x32_bf16 v[90:93], v[206:209], v[158:161], v[90:93]
	v_mfma_f32_16x16x32_bf16 v[62:65], v[206:209], v[172:175], v[62:65]
	v_mfma_f32_16x16x32_bf16 v[86:89], v[214:217], v[158:161], v[86:89]
	v_mfma_f32_16x16x32_bf16 v[54:57], v[214:217], v[172:175], v[54:57]
	v_mfma_f32_16x16x32_bf16 v[78:81], v[222:225], v[158:161], v[78:81]
	v_mfma_f32_16x16x32_bf16 v[46:49], v[222:225], v[172:175], v[46:49]
	v_mfma_f32_16x16x32_bf16 v[98:101], v[202:205], v[168:171], v[98:101]
	v_mfma_f32_16x16x32_bf16 v[70:73], v[202:205], v[194:197], v[70:73]
	v_mfma_f32_16x16x32_bf16 v[90:93], v[210:213], v[168:171], v[90:93]
	v_mfma_f32_16x16x32_bf16 v[62:65], v[210:213], v[194:197], v[62:65]
	v_mfma_f32_16x16x32_bf16 v[86:89], v[218:221], v[168:171], v[86:89]
	v_mfma_f32_16x16x32_bf16 v[54:57], v[218:221], v[194:197], v[54:57]
	v_mfma_f32_16x16x32_bf16 v[78:81], v[226:229], v[168:171], v[78:81]
	v_mfma_f32_16x16x32_bf16 v[46:49], v[226:229], v[194:197], v[46:49]
	s_setprio 0
	s_barrier
	s_add_u32 s12, s12, 0x40080
	s_addc_u32 s13, s13, 0
	s_add_i32 s0, s1, s16
	s_mov_b32 m0, s0
	v_lshl_add_u64 v[158:159], s[12:13], 0, v[132:133]
	global_load_lds_dwordx4 v[158:159], off
	s_add_i32 m0, s0, 0x2000
	v_lshl_add_u64 v[158:159], s[12:13], 0, v[130:131]
	global_load_lds_dwordx4 v[158:159], off
	s_waitcnt vmcnt(6)
	s_barrier
	s_setprio 1
	v_mfma_f32_16x16x32_bf16 v[34:37], v[198:201], v[230:233], v[34:37]
	v_mfma_f32_16x16x32_bf16 v[14:17], v[198:201], v[238:241], v[14:17]
	v_mfma_f32_16x16x32_bf16 v[26:29], v[206:209], v[230:233], v[26:29]
	v_mfma_f32_16x16x32_bf16 v[10:13], v[206:209], v[238:241], v[10:13]
	v_mfma_f32_16x16x32_bf16 v[22:25], v[214:217], v[230:233], v[22:25]
	v_mfma_f32_16x16x32_bf16 v[6:9], v[214:217], v[238:241], v[6:9]
	v_mfma_f32_16x16x32_bf16 v[18:21], v[222:225], v[230:233], v[18:21]
	v_mfma_f32_16x16x32_bf16 v[2:5], v[222:225], v[238:241], v[2:5]
	v_mfma_f32_16x16x32_bf16 v[34:37], v[202:205], v[234:237], v[34:37]
	v_mfma_f32_16x16x32_bf16 v[14:17], v[202:205], v[242:245], v[14:17]
	v_mfma_f32_16x16x32_bf16 v[26:29], v[210:213], v[234:237], v[26:29]
	v_mfma_f32_16x16x32_bf16 v[10:13], v[210:213], v[242:245], v[10:13]
	v_mfma_f32_16x16x32_bf16 v[22:25], v[218:221], v[234:237], v[22:25]
	v_mfma_f32_16x16x32_bf16 v[6:9], v[218:221], v[242:245], v[6:9]
	v_mfma_f32_16x16x32_bf16 v[18:21], v[226:229], v[234:237], v[18:21]
	v_mfma_f32_16x16x32_bf16 v[2:5], v[226:229], v[242:245], v[2:5]
	s_setprio 0
	s_add_i32 s28, s28, 2
	s_add_u32 s10, s10, 0x100
	s_addc_u32 s11, s11, 0
	s_add_u32 s22, s22, 0x100
	s_addc_u32 s23, s23, 0
	s_cmp_gt_u32 s28, 13
	s_barrier
	s_cbranch_scc0 .LBB0_161
	s_cmp_lt_i32 s95, 8
	s_mov_b64 s[10:11], -1
	s_cbranch_scc0 .LBB0_164
	s_lshl_b32 s0, s95, 2
	s_or_b32 s0, s0, s90
	s_cmp_gt_i32 s0, 15
	s_cselect_b64 s[10:11], -1, 0
	v_readlane_b32 s60, v254, 42
	v_cndmask_b32_e64 v158, v189, 1.0, s[10:11]
	s_and_b64 s[10:11], s[10:11], exec
	v_readlane_b32 s72, v254, 54
	v_readlane_b32 s73, v254, 55
	v_readlane_b32 s74, v254, 56
	v_readlane_b32 s75, v254, 57
	s_cselect_b32 s11, s75, s73
	s_cselect_b32 s10, s74, s72
	global_load_dword v159, v167, s[10:11]
	global_load_dword v169, v167, s[10:11] offset:64
	global_load_dword v170, v167, s[10:11] offset:128
	global_load_dword v171, v167, s[10:11] offset:192
	v_mov_b32_e32 v162, v126
	v_mov_b32_e32 v163, v110
	v_mov_b32_e32 v198, v127
	v_mov_b32_e32 v199, v111
	v_pk_mul_f32 v[162:163], v[162:163], v[162:163]
	v_mov_b32_e32 v194, v82
	v_mov_b32_e32 v195, v50
	v_pk_mul_f32 v[198:199], v[198:199], v[198:199]
	v_mov_b32_e32 v200, v83
	v_mov_b32_e32 v201, v51
	v_pk_mul_f32 v[194:195], v[194:195], v[194:195]
	v_pk_mul_f32 v[200:201], v[200:201], v[200:201]
	v_mov_b32_e32 v202, v198
	v_mov_b32_e32 v203, v162
	v_mov_b32_e32 v162, v199
	v_cmp_lt_i32_e32 vcc, v188, v182
	v_pk_add_f32 v[162:163], v[202:203], v[162:163]
	v_mov_b32_e32 v198, v200
	v_mov_b32_e32 v199, v194
	v_pk_add_f32 v[162:163], v[162:163], v[198:199]
	v_mov_b32_e32 v194, v201
	v_pk_add_f32 v[162:163], v[162:163], v[194:195]
	s_mov_b32 s4, 0x358637bd
	v_lshl_add_u32 v160, s5, 8, v164
	v_ashrrev_i32_e32 v161, 31, v160
	v_lshlrev_b64 v[196:197], 12, v[160:161]
	v_mov_b32_e32 v200, v129
	v_mov_b32_e32 v201, v113
	v_pk_mul_f32 v[200:201], v[200:201], v[200:201]
	v_mov_b32_e32 v202, v85
	v_mov_b32_e32 v203, v53
	v_pk_mul_f32 v[202:203], v[202:203], v[202:203]
	v_mov_b32_e32 v204, v200
	v_mov_b32_e32 v200, v202
	v_or_b32_e32 v198, 2, v160
	v_ashrrev_i32_e32 v199, 31, v198
	v_lshlrev_b64 v[198:199], 12, v[198:199]
	v_mov_b32_e32 v202, v75
	v_readlane_b32 s74, v255, 22
	v_readlane_b32 s61, v254, 43
	v_readlane_b32 s62, v254, 44
	v_readlane_b32 s63, v254, 45
	v_readlane_b32 s64, v254, 46
	v_readlane_b32 s65, v254, 47
	v_readlane_b32 s66, v254, 48
	v_readlane_b32 s67, v254, 49
	v_readlane_b32 s68, v254, 50
	v_readlane_b32 s69, v254, 51
	v_readlane_b32 s70, v254, 52
	v_readlane_b32 s71, v254, 53
	v_readlane_b32 s75, v255, 23
	s_waitcnt vmcnt(0)
	v_mul_f32_e32 v168, v158, v159
	v_mul_f32_e32 v169, v158, v169
	v_mul_f32_e32 v170, v158, v170
	s_lshl_b32 s10, s0, 6
	s_ashr_i32 s11, s10, 31
	v_mul_f32_e32 v171, v158, v171
	s_nop 0
	s_nop 0
	s_nop 0
	v_cndmask_b32_e32 v158, v180, v188, vcc
	v_lshlrev_b32_e32 v175, 2, v158
	ds_bpermute_b32 v195, v175, v163
	ds_bpermute_b32 v194, v175, v162
	v_cmp_lt_i32_e32 vcc, v187, v182
	s_waitcnt lgkmcnt(0)
	v_pk_add_f32 v[162:163], v[162:163], v[194:195]
	v_cndmask_b32_e32 v158, v180, v187, vcc
	v_lshlrev_b32_e32 v174, 2, v158
	ds_bpermute_b32 v195, v174, v163
	ds_bpermute_b32 v194, v174, v162
	v_cmp_lt_i32_e32 vcc, v186, v182
	s_waitcnt lgkmcnt(0)
; __device__ __forceinline__ unsigned f2bf(float f) { const __bf16 b = (__bf16)f; return (unsigned)__builtin_bit_cast(unsigned short, b); }
;     __device__ __forceinline__ void operator()(Acc& acc, int pm, int pn, int wr, int wc, int fr, int fq) const {
;     ...
;                     float ss = acc[ai][0][m][0][j] * acc[ai][0][m][0][j] + acc[ai][0][m][1][j] * acc[ai][0][m][1][j] +
;                                acc[ai][1][m][0][j] * acc[ai][1][m][0][j] + acc[ai][1][m][1][j] * acc[ai][1][m][1][j];
;                     ss += __shfl_xor(ss, 1); ss += __shfl_xor(ss, 2); ss += __shfl_xor(ss, 4); ss += __shfl_xor(ss, 8);
;                     const float rs = rsqrtf(ss * (1.0f / 64.0f) + EPSV);
;                     bf16_t* rp = qk + (size_t)(pm * 256 + ai * 128 + wr * 64 + m * 16 + fq * 4 + j) * 2048 + head * 64 + fr;
; #pragma unroll
;                     for (int bj = 0; bj < 2; ++bj)
; #pragma unroll
;                         for (int n = 0; n < 2; ++n) rp[bj * 32 + n * 16] = (bf16_t)f2bf(acc[ai][bj][m][n][j] * rs * gv[bj][n]);
;                 }
	v_pk_add_f32 v[162:163], v[162:163], v[194:195]
	v_cndmask_b32_e32 v158, v180, v186, vcc
	v_lshlrev_b32_e32 v173, 2, v158
	ds_bpermute_b32 v195, v173, v163
	ds_bpermute_b32 v194, v173, v162
	v_cmp_lt_i32_e32 vcc, v185, v182
	s_waitcnt lgkmcnt(0)
	v_pk_add_f32 v[162:163], v[162:163], v[194:195]
	v_cndmask_b32_e32 v158, v180, v185, vcc
	v_lshlrev_b32_e32 v172, 2, v158
	ds_bpermute_b32 v195, v172, v163
	ds_bpermute_b32 v194, v172, v162
	v_lshl_add_u64 v[158:159], s[10:11], 1, v[150:151]
	v_lshl_add_u64 v[196:197], v[158:159], 0, v[196:197]
	v_lshl_add_u64 v[198:199], v[158:159], 0, v[198:199]
	s_mov_b64 s[10:11], 0
	s_waitcnt lgkmcnt(0)
	v_pk_add_f32 v[194:195], v[162:163], v[194:195]
	v_mov_b64_e32 v[162:163], s[4:5]
	v_pk_fma_f32 v[194:195], v[194:195], s[8:9], v[162:163] op_sel_hi:[1,0,0]
	s_nop 0
	v_mul_f32_e32 v161, 0x4b800000, v195
	v_cmp_gt_f32_e64 s[46:47], s93, v195
	v_cmp_gt_f32_e32 vcc, s93, v194
	s_nop 0
	v_cndmask_b32_e64 v161, v195, v161, s[46:47]
	v_rsq_f32_e32 v161, v161
	s_nop 0
	v_mul_f32_e32 v192, 0x45800000, v161
	v_cndmask_b32_e64 v161, v161, v192, s[46:47]
	v_mul_f32_e32 v192, v126, v161
	v_mul_f32_e32 v192, v168, v192
	v_cvt_pk_bf16_f32 v192, v192, s0
	global_store_short v[196:197], v192, off
	v_mul_f32_e32 v192, v110, v161
	v_mul_f32_e32 v192, v169, v192
	v_cvt_pk_bf16_f32 v192, v192, s0
	global_store_short v[196:197], v192, off offset:32
	v_mul_f32_e32 v192, v82, v161
	v_mul_f32_e32 v161, v50, v161
	v_mul_f32_e32 v161, v171, v161
	v_cvt_pk_bf16_f32 v161, v161, s0
	global_store_short v[196:197], v161, off offset:96
	v_mul_f32_e32 v161, 0x4b800000, v194
	v_cndmask_b32_e32 v161, v194, v161, vcc
	v_rsq_f32_e32 v161, v161
	v_mul_f32_e32 v192, v170, v192
	v_cvt_pk_bf16_f32 v192, v192, s0
	global_store_short v[196:197], v192, off offset:64
	v_mul_f32_e32 v192, 0x45800000, v161
	v_cndmask_b32_e32 v161, v161, v192, vcc
	v_or_b32_e32 v194, 1, v160
	v_ashrrev_i32_e32 v195, 31, v194
	v_mul_f32_e32 v192, v127, v161
	v_lshlrev_b64 v[194:195], 12, v[194:195]
	v_mul_f32_e32 v192, v168, v192
	v_lshl_add_u64 v[194:195], v[158:159], 0, v[194:195]
	v_cvt_pk_bf16_f32 v192, v192, s0
	global_store_short v[194:195], v192, off
	v_mul_f32_e32 v192, v111, v161
	v_mul_f32_e32 v192, v169, v192
	v_cvt_pk_bf16_f32 v192, v192, s0
	global_store_short v[194:195], v192, off offset:32
	v_mul_f32_e32 v192, v83, v161
	v_mul_f32_e32 v161, v51, v161
	v_mul_f32_e32 v192, v170, v192
	v_mul_f32_e32 v161, v171, v161
	v_cvt_pk_bf16_f32 v192, v192, s0
	v_cvt_pk_bf16_f32 v161, v161, s0
	global_store_short v[194:195], v192, off offset:64
	global_store_short v[194:195], v161, off offset:96
	v_mov_b32_e32 v194, v128
	v_mov_b32_e32 v195, v112
	v_pk_mul_f32 v[194:195], v[194:195], v[194:195]
	v_mov_b32_e32 v196, v84
	v_mov_b32_e32 v197, v52
	v_pk_mul_f32 v[196:197], v[196:197], v[196:197]
	v_mov_b32_e32 v205, v194
	v_mov_b32_e32 v194, v201
	v_pk_add_f32 v[194:195], v[204:205], v[194:195]
	v_mov_b32_e32 v201, v196
	v_pk_add_f32 v[194:195], v[194:195], v[200:201]
	v_mov_b32_e32 v196, v203
	v_pk_add_f32 v[194:195], v[194:195], v[196:197]
	ds_bpermute_b32 v197, v175, v195
	ds_bpermute_b32 v196, v175, v194
	v_mov_b32_e32 v200, v123
	v_mov_b32_e32 v201, v107
	v_pk_mul_f32 v[200:201], v[200:201], v[200:201]
	v_mov_b32_e32 v203, v43
	s_waitcnt lgkmcnt(0)
	v_pk_add_f32 v[194:195], v[194:195], v[196:197]
	ds_bpermute_b32 v197, v174, v195
	ds_bpermute_b32 v196, v174, v194
	v_pk_mul_f32 v[202:203], v[202:203], v[202:203]
	v_mov_b32_e32 v204, v200
	v_mov_b32_e32 v200, v202
	v_mov_b32_e32 v202, v77
	s_waitcnt lgkmcnt(0)
	v_pk_add_f32 v[194:195], v[194:195], v[196:197]
	ds_bpermute_b32 v197, v173, v195
	ds_bpermute_b32 v196, v173, v194
	s_waitcnt lgkmcnt(0)
	v_pk_add_f32 v[194:195], v[194:195], v[196:197]
	ds_bpermute_b32 v197, v172, v195
	ds_bpermute_b32 v196, v172, v194
	s_waitcnt lgkmcnt(0)
	v_pk_add_f32 v[194:195], v[194:195], v[196:197]
	s_nop 0
	v_pk_fma_f32 v[194:195], v[194:195], s[8:9], v[162:163] op_sel_hi:[1,0,0]
	v_mov_b32_e32 v196, v122
	v_mul_f32_e32 v161, 0x4b800000, v195
	v_cmp_gt_f32_e64 s[46:47], s93, v195
	v_mov_b32_e32 v197, v106
	v_pk_mul_f32 v[196:197], v[196:197], v[196:197]
	v_cndmask_b32_e64 v161, v195, v161, s[46:47]
	v_rsq_f32_e32 v161, v161
	v_mov_b32_e32 v205, v196
	v_mov_b32_e32 v196, v201
	v_pk_add_f32 v[196:197], v[204:205], v[196:197]
	v_mul_f32_e32 v192, 0x45800000, v161
	v_cndmask_b32_e64 v161, v161, v192, s[46:47]
	v_mul_f32_e32 v192, v128, v161
	v_mul_f32_e32 v192, v168, v192
	v_cvt_pk_bf16_f32 v192, v192, s0
	global_store_short v[198:199], v192, off
	v_mul_f32_e32 v192, v112, v161
	v_mul_f32_e32 v192, v169, v192
	v_cvt_pk_bf16_f32 v192, v192, s0
	global_store_short v[198:199], v192, off offset:32
	v_mul_f32_e32 v192, v84, v161
	v_mul_f32_e32 v161, v52, v161
	v_mul_f32_e32 v192, v170, v192
	v_mul_f32_e32 v161, v171, v161
	v_cvt_pk_bf16_f32 v192, v192, s0
	v_cvt_pk_bf16_f32 v161, v161, s0
	global_store_short v[198:199], v192, off offset:64
	global_store_short v[198:199], v161, off offset:96
	v_mov_b32_e32 v198, v74
	v_mov_b32_e32 v199, v42
	v_pk_mul_f32 v[198:199], v[198:199], v[198:199]
	v_cmp_gt_f32_e32 vcc, s93, v194
	v_mov_b32_e32 v201, v198
	v_pk_add_f32 v[196:197], v[196:197], v[200:201]
	v_mov_b32_e32 v198, v203
	v_pk_add_f32 v[196:197], v[196:197], v[198:199]
	ds_bpermute_b32 v199, v175, v197
	ds_bpermute_b32 v198, v175, v196
	v_mul_f32_e32 v161, 0x4b800000, v194
	v_cndmask_b32_e32 v161, v194, v161, vcc
	v_rsq_f32_e32 v161, v161
	v_or_b32_e32 v194, 3, v160
	s_waitcnt lgkmcnt(0)
	v_pk_add_f32 v[196:197], v[196:197], v[198:199]
	ds_bpermute_b32 v199, v174, v197
	ds_bpermute_b32 v198, v174, v196
	v_mul_f32_e32 v192, 0x45800000, v161
	v_cndmask_b32_e32 v161, v161, v192, vcc
	v_ashrrev_i32_e32 v195, 31, v194
	v_mul_f32_e32 v192, v129, v161
	s_waitcnt lgkmcnt(0)
; __device__ __forceinline__ unsigned f2bf(float f) { const __bf16 b = (__bf16)f; return (unsigned)__builtin_bit_cast(unsigned short, b); }
;     __device__ __forceinline__ void operator()(Acc& acc, int pm, int pn, int wr, int wc, int fr, int fq) const {
;     ...
; #pragma unroll
;         for (int ai = 0; ai < 2; ++ai)
; #pragma unroll
;             for (int m = 0; m < 4; ++m)
; #pragma unroll
;                 for (int j = 0; j < 4; ++j) {
;                     float ss = acc[ai][0][m][0][j] * acc[ai][0][m][0][j] + acc[ai][0][m][1][j] * acc[ai][0][m][1][j] +
;                                acc[ai][1][m][0][j] * acc[ai][1][m][0][j] + acc[ai][1][m][1][j] * acc[ai][1][m][1][j];
;                     ss += __shfl_xor(ss, 1); ss += __shfl_xor(ss, 2); ss += __shfl_xor(ss, 4); ss += __shfl_xor(ss, 8);
;                     const float rs = rsqrtf(ss * (1.0f / 64.0f) + EPSV);
;                     bf16_t* rp = qk + (size_t)(pm * 256 + ai * 128 + wr * 64 + m * 16 + fq * 4 + j) * 2048 + head * 64 + fr;
; #pragma unroll
;                     for (int bj = 0; bj < 2; ++bj)
; #pragma unroll
;                         for (int n = 0; n < 2; ++n) rp[bj * 32 + n * 16] = (bf16_t)f2bf(acc[ai][bj][m][n][j] * rs * gv[bj][n]);
;                 }
	v_pk_add_f32 v[196:197], v[196:197], v[198:199]
	ds_bpermute_b32 v199, v173, v197
	ds_bpermute_b32 v198, v173, v196
	v_lshlrev_b64 v[194:195], 12, v[194:195]
	v_mul_f32_e32 v192, v168, v192
	v_lshl_add_u64 v[194:195], v[158:159], 0, v[194:195]
	v_cvt_pk_bf16_f32 v192, v192, s0
	s_waitcnt lgkmcnt(0)
	v_pk_add_f32 v[196:197], v[196:197], v[198:199]
	ds_bpermute_b32 v199, v172, v197
	ds_bpermute_b32 v198, v172, v196
	global_store_short v[194:195], v192, off
	v_mul_f32_e32 v192, v113, v161
	v_mul_f32_e32 v192, v169, v192
	v_cvt_pk_bf16_f32 v192, v192, s0
	global_store_short v[194:195], v192, off offset:32
	v_mul_f32_e32 v192, v85, v161
	v_mul_f32_e32 v161, v53, v161
	v_mul_f32_e32 v161, v171, v161
	s_waitcnt lgkmcnt(0)
	v_pk_add_f32 v[196:197], v[196:197], v[198:199]
	v_cvt_pk_bf16_f32 v161, v161, s0
	v_pk_fma_f32 v[196:197], v[196:197], s[8:9], v[162:163] op_sel_hi:[1,0,0]
	global_store_short v[194:195], v161, off offset:96
	v_mul_f32_e32 v161, 0x4b800000, v197
	v_cmp_gt_f32_e64 s[46:47], s93, v197
	v_mul_f32_e32 v192, v170, v192
	v_cvt_pk_bf16_f32 v192, v192, s0
	v_cndmask_b32_e64 v161, v197, v161, s[46:47]
	v_rsq_f32_e32 v161, v161
	global_store_short v[194:195], v192, off offset:64
	v_or_b32_e32 v194, 16, v160
	v_ashrrev_i32_e32 v195, 31, v194
	v_mul_f32_e32 v192, 0x45800000, v161
	v_cndmask_b32_e64 v161, v161, v192, s[46:47]
	v_mul_f32_e32 v192, v122, v161
	v_lshlrev_b64 v[194:195], 12, v[194:195]
	v_mul_f32_e32 v192, v168, v192
	v_lshl_add_u64 v[194:195], v[158:159], 0, v[194:195]
	v_cvt_pk_bf16_f32 v192, v192, s0
	global_store_short v[194:195], v192, off
	v_mul_f32_e32 v192, v106, v161
	v_mul_f32_e32 v192, v169, v192
	v_cvt_pk_bf16_f32 v192, v192, s0
	global_store_short v[194:195], v192, off offset:32
	v_mul_f32_e32 v192, v74, v161
	v_mul_f32_e32 v161, v42, v161
	v_mul_f32_e32 v161, v171, v161
	v_cvt_pk_bf16_f32 v161, v161, s0
	v_cmp_gt_f32_e32 vcc, s93, v196
	global_store_short v[194:195], v161, off offset:96
	v_mul_f32_e32 v161, 0x4b800000, v196
	v_cndmask_b32_e32 v161, v196, v161, vcc
	v_rsq_f32_e32 v161, v161
	v_mul_f32_e32 v192, v170, v192
	v_cvt_pk_bf16_f32 v192, v192, s0
	global_store_short v[194:195], v192, off offset:64
	v_mul_f32_e32 v192, 0x45800000, v161
	v_cndmask_b32_e32 v161, v161, v192, vcc
	v_or_b32_e32 v194, 17, v160
	v_ashrrev_i32_e32 v195, 31, v194
	v_mul_f32_e32 v192, v123, v161
	v_lshlrev_b64 v[194:195], 12, v[194:195]
	v_mul_f32_e32 v192, v168, v192
	v_lshl_add_u64 v[194:195], v[158:159], 0, v[194:195]
	v_cvt_pk_bf16_f32 v192, v192, s0
	global_store_short v[194:195], v192, off
	v_mul_f32_e32 v192, v107, v161
	v_mul_f32_e32 v192, v169, v192
	v_cvt_pk_bf16_f32 v192, v192, s0
	global_store_short v[194:195], v192, off offset:32
	v_mul_f32_e32 v192, v75, v161
	v_mul_f32_e32 v161, v43, v161
	v_mul_f32_e32 v192, v170, v192
	v_mul_f32_e32 v161, v171, v161
	v_cvt_pk_bf16_f32 v192, v192, s0
	v_cvt_pk_bf16_f32 v161, v161, s0
	global_store_short v[194:195], v192, off offset:64
	global_store_short v[194:195], v161, off offset:96
	v_mov_b32_e32 v194, v124
	v_mov_b32_e32 v195, v108
	v_mov_b32_e32 v200, v125
	v_mov_b32_e32 v201, v109
	v_pk_mul_f32 v[194:195], v[194:195], v[194:195]
	v_mov_b32_e32 v196, v76
	v_mov_b32_e32 v197, v44
	v_pk_mul_f32 v[200:201], v[200:201], v[200:201]
	v_mov_b32_e32 v203, v45
	v_pk_mul_f32 v[196:197], v[196:197], v[196:197]
	v_pk_mul_f32 v[202:203], v[202:203], v[202:203]
	v_mov_b32_e32 v204, v200
	v_mov_b32_e32 v205, v194
	v_mov_b32_e32 v194, v201
	v_pk_add_f32 v[194:195], v[204:205], v[194:195]
	v_mov_b32_e32 v200, v202
	v_mov_b32_e32 v201, v196
	v_pk_add_f32 v[194:195], v[194:195], v[200:201]
	v_mov_b32_e32 v196, v203
	v_pk_add_f32 v[194:195], v[194:195], v[196:197]
	ds_bpermute_b32 v197, v175, v195
	ds_bpermute_b32 v196, v175, v194
	v_or_b32_e32 v198, 18, v160
	v_ashrrev_i32_e32 v199, 31, v198
	v_lshlrev_b64 v[198:199], 12, v[198:199]
	v_lshl_add_u64 v[198:199], v[158:159], 0, v[198:199]
	s_waitcnt lgkmcnt(0)
	v_pk_add_f32 v[194:195], v[194:195], v[196:197]
	ds_bpermute_b32 v197, v174, v195
	ds_bpermute_b32 v196, v174, v194
	v_mov_b32_e32 v200, v119
	v_mov_b32_e32 v201, v103
	v_pk_mul_f32 v[200:201], v[200:201], v[200:201]
	v_mov_b32_e32 v202, v67
	s_waitcnt lgkmcnt(0)
	v_pk_add_f32 v[194:195], v[194:195], v[196:197]
	ds_bpermute_b32 v197, v173, v195
	ds_bpermute_b32 v196, v173, v194
	v_mov_b32_e32 v203, v39
	v_pk_mul_f32 v[202:203], v[202:203], v[202:203]
	v_mov_b32_e32 v204, v200
	v_mov_b32_e32 v200, v202
	s_waitcnt lgkmcnt(0)
	v_pk_add_f32 v[194:195], v[194:195], v[196:197]
	ds_bpermute_b32 v197, v172, v195
	ds_bpermute_b32 v196, v172, v194
	v_mov_b32_e32 v202, v69
	s_waitcnt lgkmcnt(0)
	v_pk_add_f32 v[194:195], v[194:195], v[196:197]
	s_nop 0
	v_pk_fma_f32 v[194:195], v[194:195], s[8:9], v[162:163] op_sel_hi:[1,0,0]
	v_mov_b32_e32 v196, v118
	v_mul_f32_e32 v161, 0x4b800000, v195
	v_cmp_gt_f32_e64 s[46:47], s93, v195
	v_mov_b32_e32 v197, v102
	v_pk_mul_f32 v[196:197], v[196:197], v[196:197]
	v_cndmask_b32_e64 v161, v195, v161, s[46:47]
	v_rsq_f32_e32 v161, v161
	v_mov_b32_e32 v205, v196
	v_mov_b32_e32 v196, v201
	v_pk_add_f32 v[196:197], v[204:205], v[196:197]
	v_mul_f32_e32 v192, 0x45800000, v161
	v_cndmask_b32_e64 v161, v161, v192, s[46:47]
	v_mul_f32_e32 v192, v124, v161
	v_mul_f32_e32 v192, v168, v192
	v_cvt_pk_bf16_f32 v192, v192, s0
	global_store_short v[198:199], v192, off
	v_mul_f32_e32 v192, v108, v161
	v_mul_f32_e32 v192, v169, v192
	v_cvt_pk_bf16_f32 v192, v192, s0
	global_store_short v[198:199], v192, off offset:32
	v_mul_f32_e32 v192, v76, v161
	v_mul_f32_e32 v161, v44, v161
	v_mul_f32_e32 v192, v170, v192
	v_mul_f32_e32 v161, v171, v161
	v_cvt_pk_bf16_f32 v192, v192, s0
	v_cvt_pk_bf16_f32 v161, v161, s0
	global_store_short v[198:199], v192, off offset:64
	global_store_short v[198:199], v161, off offset:96
	v_mov_b32_e32 v198, v66
	v_mov_b32_e32 v199, v38
	v_pk_mul_f32 v[198:199], v[198:199], v[198:199]
	v_cmp_gt_f32_e32 vcc, s93, v194
	v_mov_b32_e32 v201, v198
	v_pk_add_f32 v[196:197], v[196:197], v[200:201]
	v_mov_b32_e32 v198, v203
	v_pk_add_f32 v[196:197], v[196:197], v[198:199]
	ds_bpermute_b32 v199, v175, v197
	ds_bpermute_b32 v198, v175, v196
	v_mul_f32_e32 v161, 0x4b800000, v194
	v_cndmask_b32_e32 v161, v194, v161, vcc
	v_rsq_f32_e32 v161, v161
	v_or_b32_e32 v194, 19, v160
	s_waitcnt lgkmcnt(0)
; __device__ __forceinline__ unsigned f2bf(float f) { const __bf16 b = (__bf16)f; return (unsigned)__builtin_bit_cast(unsigned short, b); }
;     __device__ __forceinline__ void operator()(Acc& acc, int pm, int pn, int wr, int wc, int fr, int fq) const {
;     ...
; #pragma unroll
;         for (int ai = 0; ai < 2; ++ai)
; #pragma unroll
;             for (int m = 0; m < 4; ++m)
; #pragma unroll
;                 for (int j = 0; j < 4; ++j) {
;                     float ss = acc[ai][0][m][0][j] * acc[ai][0][m][0][j] + acc[ai][0][m][1][j] * acc[ai][0][m][1][j] +
;                                acc[ai][1][m][0][j] * acc[ai][1][m][0][j] + acc[ai][1][m][1][j] * acc[ai][1][m][1][j];
;                     ss += __shfl_xor(ss, 1); ss += __shfl_xor(ss, 2); ss += __shfl_xor(ss, 4); ss += __shfl_xor(ss, 8);
;                     const float rs = rsqrtf(ss * (1.0f / 64.0f) + EPSV);
;                     bf16_t* rp = qk + (size_t)(pm * 256 + ai * 128 + wr * 64 + m * 16 + fq * 4 + j) * 2048 + head * 64 + fr;
; #pragma unroll
;                     for (int bj = 0; bj < 2; ++bj)
; #pragma unroll
;                         for (int n = 0; n < 2; ++n) rp[bj * 32 + n * 16] = (bf16_t)f2bf(acc[ai][bj][m][n][j] * rs * gv[bj][n]);
;                 }
	v_pk_add_f32 v[196:197], v[196:197], v[198:199]
	ds_bpermute_b32 v199, v174, v197
	ds_bpermute_b32 v198, v174, v196
	v_mul_f32_e32 v192, 0x45800000, v161
	v_cndmask_b32_e32 v161, v161, v192, vcc
	v_ashrrev_i32_e32 v195, 31, v194
	v_mul_f32_e32 v192, v125, v161
	s_waitcnt lgkmcnt(0)
	v_pk_add_f32 v[196:197], v[196:197], v[198:199]
	ds_bpermute_b32 v199, v173, v197
	ds_bpermute_b32 v198, v173, v196
	v_lshlrev_b64 v[194:195], 12, v[194:195]
	v_mul_f32_e32 v192, v168, v192
	v_lshl_add_u64 v[194:195], v[158:159], 0, v[194:195]
	v_cvt_pk_bf16_f32 v192, v192, s0
	s_waitcnt lgkmcnt(0)
	v_pk_add_f32 v[196:197], v[196:197], v[198:199]
	ds_bpermute_b32 v199, v172, v197
	ds_bpermute_b32 v198, v172, v196
	global_store_short v[194:195], v192, off
	v_mul_f32_e32 v192, v109, v161
	v_mul_f32_e32 v192, v169, v192
	v_cvt_pk_bf16_f32 v192, v192, s0
	global_store_short v[194:195], v192, off offset:32
	v_mul_f32_e32 v192, v77, v161
	v_mul_f32_e32 v161, v45, v161
	v_mul_f32_e32 v161, v171, v161
	s_waitcnt lgkmcnt(0)
	v_pk_add_f32 v[196:197], v[196:197], v[198:199]
	v_cvt_pk_bf16_f32 v161, v161, s0
	v_pk_fma_f32 v[196:197], v[196:197], s[8:9], v[162:163] op_sel_hi:[1,0,0]
	global_store_short v[194:195], v161, off offset:96
	v_mul_f32_e32 v161, 0x4b800000, v197
	v_cmp_gt_f32_e64 s[46:47], s93, v197
	v_mul_f32_e32 v192, v170, v192
	v_cvt_pk_bf16_f32 v192, v192, s0
	v_cndmask_b32_e64 v161, v197, v161, s[46:47]
	v_rsq_f32_e32 v161, v161
	global_store_short v[194:195], v192, off offset:64
	v_or_b32_e32 v194, 32, v160
	v_ashrrev_i32_e32 v195, 31, v194
	v_mul_f32_e32 v192, 0x45800000, v161
	v_cndmask_b32_e64 v161, v161, v192, s[46:47]
	v_mul_f32_e32 v192, v118, v161
	v_lshlrev_b64 v[194:195], 12, v[194:195]
	v_mul_f32_e32 v192, v168, v192
	v_lshl_add_u64 v[194:195], v[158:159], 0, v[194:195]
	v_cvt_pk_bf16_f32 v192, v192, s0
	global_store_short v[194:195], v192, off
	v_mul_f32_e32 v192, v102, v161
	v_mul_f32_e32 v192, v169, v192
	v_cvt_pk_bf16_f32 v192, v192, s0
	global_store_short v[194:195], v192, off offset:32
	v_mul_f32_e32 v192, v66, v161
	v_mul_f32_e32 v161, v38, v161
	v_mul_f32_e32 v161, v171, v161
	v_cvt_pk_bf16_f32 v161, v161, s0
	v_cmp_gt_f32_e32 vcc, s93, v196
	global_store_short v[194:195], v161, off offset:96
	v_mul_f32_e32 v161, 0x4b800000, v196
	v_cndmask_b32_e32 v161, v196, v161, vcc
	v_rsq_f32_e32 v161, v161
	v_mul_f32_e32 v192, v170, v192
	v_cvt_pk_bf16_f32 v192, v192, s0
	global_store_short v[194:195], v192, off offset:64
	v_mul_f32_e32 v192, 0x45800000, v161
	v_cndmask_b32_e32 v161, v161, v192, vcc
	v_or_b32_e32 v194, 33, v160
	v_ashrrev_i32_e32 v195, 31, v194
	v_mul_f32_e32 v192, v119, v161
	v_lshlrev_b64 v[194:195], 12, v[194:195]
	v_mul_f32_e32 v192, v168, v192
	v_lshl_add_u64 v[194:195], v[158:159], 0, v[194:195]
	v_cvt_pk_bf16_f32 v192, v192, s0
	global_store_short v[194:195], v192, off
	v_mul_f32_e32 v192, v103, v161
	v_mul_f32_e32 v192, v169, v192
	v_cvt_pk_bf16_f32 v192, v192, s0
	global_store_short v[194:195], v192, off offset:32
	v_mul_f32_e32 v192, v67, v161
	v_mul_f32_e32 v161, v39, v161
	v_mul_f32_e32 v192, v170, v192
	v_mul_f32_e32 v161, v171, v161
	v_cvt_pk_bf16_f32 v192, v192, s0
	v_cvt_pk_bf16_f32 v161, v161, s0
	global_store_short v[194:195], v192, off offset:64
	global_store_short v[194:195], v161, off offset:96
	v_mov_b32_e32 v194, v120
	v_mov_b32_e32 v195, v104
	v_mov_b32_e32 v200, v121
	v_mov_b32_e32 v201, v105
	v_pk_mul_f32 v[194:195], v[194:195], v[194:195]
	v_mov_b32_e32 v196, v68
	v_mov_b32_e32 v197, v40
	v_pk_mul_f32 v[200:201], v[200:201], v[200:201]
	v_mov_b32_e32 v203, v41
	v_pk_mul_f32 v[196:197], v[196:197], v[196:197]
	v_pk_mul_f32 v[202:203], v[202:203], v[202:203]
	v_mov_b32_e32 v204, v200
	v_mov_b32_e32 v205, v194
	v_mov_b32_e32 v194, v201
	v_pk_add_f32 v[194:195], v[204:205], v[194:195]
	v_mov_b32_e32 v200, v202
	v_mov_b32_e32 v201, v196
	v_pk_add_f32 v[194:195], v[194:195], v[200:201]
	v_mov_b32_e32 v196, v203
	v_pk_add_f32 v[194:195], v[194:195], v[196:197]
	ds_bpermute_b32 v197, v175, v195
	ds_bpermute_b32 v196, v175, v194
	v_or_b32_e32 v198, 34, v160
	v_ashrrev_i32_e32 v199, 31, v198
	v_lshlrev_b64 v[198:199], 12, v[198:199]
	v_lshl_add_u64 v[198:199], v[158:159], 0, v[198:199]
	s_waitcnt lgkmcnt(0)
	v_pk_add_f32 v[194:195], v[194:195], v[196:197]
	ds_bpermute_b32 v197, v174, v195
	ds_bpermute_b32 v196, v174, v194
	v_mov_b32_e32 v200, v115
	v_mov_b32_e32 v201, v95
	v_pk_mul_f32 v[200:201], v[200:201], v[200:201]
	v_mov_b32_e32 v202, v59
	s_waitcnt lgkmcnt(0)
	v_pk_add_f32 v[194:195], v[194:195], v[196:197]
	ds_bpermute_b32 v197, v173, v195
	ds_bpermute_b32 v196, v173, v194
	v_mov_b32_e32 v203, v31
	v_pk_mul_f32 v[202:203], v[202:203], v[202:203]
	v_mov_b32_e32 v204, v200
	v_mov_b32_e32 v200, v202
	s_waitcnt lgkmcnt(0)
	v_pk_add_f32 v[194:195], v[194:195], v[196:197]
	ds_bpermute_b32 v197, v172, v195
	ds_bpermute_b32 v196, v172, v194
	v_mov_b32_e32 v202, v61
	s_waitcnt lgkmcnt(0)
; __device__ __forceinline__ unsigned f2bf(float f) { const __bf16 b = (__bf16)f; return (unsigned)__builtin_bit_cast(unsigned short, b); }
;     __device__ __forceinline__ void operator()(Acc& acc, int pm, int pn, int wr, int wc, int fr, int fq) const {
;     ...
; #pragma unroll
;         for (int ai = 0; ai < 2; ++ai)
; #pragma unroll
;             for (int m = 0; m < 4; ++m)
; #pragma unroll
;                 for (int j = 0; j < 4; ++j) {
;                     float ss = acc[ai][0][m][0][j] * acc[ai][0][m][0][j] + acc[ai][0][m][1][j] * acc[ai][0][m][1][j] +
;                                acc[ai][1][m][0][j] * acc[ai][1][m][0][j] + acc[ai][1][m][1][j] * acc[ai][1][m][1][j];
;                     ss += __shfl_xor(ss, 1); ss += __shfl_xor(ss, 2); ss += __shfl_xor(ss, 4); ss += __shfl_xor(ss, 8);
;                     const float rs = rsqrtf(ss * (1.0f / 64.0f) + EPSV);
;                     bf16_t* rp = qk + (size_t)(pm * 256 + ai * 128 + wr * 64 + m * 16 + fq * 4 + j) * 2048 + head * 64 + fr;
; #pragma unroll
;                     for (int bj = 0; bj < 2; ++bj)
; #pragma unroll
;                         for (int n = 0; n < 2; ++n) rp[bj * 32 + n * 16] = (bf16_t)f2bf(acc[ai][bj][m][n][j] * rs * gv[bj][n]);
;                 }
	v_pk_add_f32 v[194:195], v[194:195], v[196:197]
	s_nop 0
	v_pk_fma_f32 v[194:195], v[194:195], s[8:9], v[162:163] op_sel_hi:[1,0,0]
	v_mov_b32_e32 v196, v114
	v_mul_f32_e32 v161, 0x4b800000, v195
	v_cmp_gt_f32_e64 s[46:47], s93, v195
	v_mov_b32_e32 v197, v94
	v_pk_mul_f32 v[196:197], v[196:197], v[196:197]
	v_cndmask_b32_e64 v161, v195, v161, s[46:47]
	v_rsq_f32_e32 v161, v161
	v_mov_b32_e32 v205, v196
	v_mov_b32_e32 v196, v201
	v_pk_add_f32 v[196:197], v[204:205], v[196:197]
	v_mul_f32_e32 v192, 0x45800000, v161
	v_cndmask_b32_e64 v161, v161, v192, s[46:47]
	v_mul_f32_e32 v192, v120, v161
	v_mul_f32_e32 v192, v168, v192
	v_cvt_pk_bf16_f32 v192, v192, s0
	global_store_short v[198:199], v192, off
	v_mul_f32_e32 v192, v104, v161
	v_mul_f32_e32 v192, v169, v192
	v_cvt_pk_bf16_f32 v192, v192, s0
	global_store_short v[198:199], v192, off offset:32
	v_mul_f32_e32 v192, v68, v161
	v_mul_f32_e32 v161, v40, v161
	v_mul_f32_e32 v192, v170, v192
	v_mul_f32_e32 v161, v171, v161
	v_cvt_pk_bf16_f32 v192, v192, s0
	v_cvt_pk_bf16_f32 v161, v161, s0
	global_store_short v[198:199], v192, off offset:64
	global_store_short v[198:199], v161, off offset:96
	v_mov_b32_e32 v198, v58
	v_mov_b32_e32 v199, v30
	v_pk_mul_f32 v[198:199], v[198:199], v[198:199]
	v_cmp_gt_f32_e32 vcc, s93, v194
	v_mov_b32_e32 v201, v198
	v_pk_add_f32 v[196:197], v[196:197], v[200:201]
	v_mov_b32_e32 v198, v203
	v_pk_add_f32 v[196:197], v[196:197], v[198:199]
	ds_bpermute_b32 v199, v175, v197
	ds_bpermute_b32 v198, v175, v196
	v_mul_f32_e32 v161, 0x4b800000, v194
	v_cndmask_b32_e32 v161, v194, v161, vcc
	v_rsq_f32_e32 v161, v161
	v_or_b32_e32 v194, 35, v160
	s_waitcnt lgkmcnt(0)
	v_pk_add_f32 v[196:197], v[196:197], v[198:199]
	ds_bpermute_b32 v199, v174, v197
	ds_bpermute_b32 v198, v174, v196
	v_mul_f32_e32 v192, 0x45800000, v161
	v_cndmask_b32_e32 v161, v161, v192, vcc
	v_ashrrev_i32_e32 v195, 31, v194
	v_mul_f32_e32 v192, v121, v161
	s_waitcnt lgkmcnt(0)
	v_pk_add_f32 v[196:197], v[196:197], v[198:199]
	ds_bpermute_b32 v199, v173, v197
	ds_bpermute_b32 v198, v173, v196
	v_lshlrev_b64 v[194:195], 12, v[194:195]
	v_mul_f32_e32 v192, v168, v192
	v_lshl_add_u64 v[194:195], v[158:159], 0, v[194:195]
	v_cvt_pk_bf16_f32 v192, v192, s0
	s_waitcnt lgkmcnt(0)
	v_pk_add_f32 v[196:197], v[196:197], v[198:199]
	ds_bpermute_b32 v199, v172, v197
	ds_bpermute_b32 v198, v172, v196
	global_store_short v[194:195], v192, off
	v_mul_f32_e32 v192, v105, v161
	v_mul_f32_e32 v192, v169, v192
	v_cvt_pk_bf16_f32 v192, v192, s0
	global_store_short v[194:195], v192, off offset:32
	v_mul_f32_e32 v192, v69, v161
	v_mul_f32_e32 v161, v41, v161
	v_mul_f32_e32 v161, v171, v161
	s_waitcnt lgkmcnt(0)
	v_pk_add_f32 v[196:197], v[196:197], v[198:199]
	v_cvt_pk_bf16_f32 v161, v161, s0
	v_pk_fma_f32 v[196:197], v[196:197], s[8:9], v[162:163] op_sel_hi:[1,0,0]
	global_store_short v[194:195], v161, off offset:96
	v_mul_f32_e32 v161, 0x4b800000, v197
	v_cmp_gt_f32_e64 s[46:47], s93, v197
	v_mul_f32_e32 v192, v170, v192
	v_cvt_pk_bf16_f32 v192, v192, s0
	v_cndmask_b32_e64 v161, v197, v161, s[46:47]
	v_rsq_f32_e32 v161, v161
	global_store_short v[194:195], v192, off offset:64
	v_or_b32_e32 v194, 48, v160
	v_ashrrev_i32_e32 v195, 31, v194
	v_mul_f32_e32 v192, 0x45800000, v161
	v_cndmask_b32_e64 v161, v161, v192, s[46:47]
	v_mul_f32_e32 v192, v114, v161
	v_lshlrev_b64 v[194:195], 12, v[194:195]
	v_mul_f32_e32 v192, v168, v192
	v_lshl_add_u64 v[194:195], v[158:159], 0, v[194:195]
	v_cvt_pk_bf16_f32 v192, v192, s0
	global_store_short v[194:195], v192, off
	v_mul_f32_e32 v192, v94, v161
	v_mul_f32_e32 v192, v169, v192
	v_cvt_pk_bf16_f32 v192, v192, s0
	global_store_short v[194:195], v192, off offset:32
	v_mul_f32_e32 v192, v58, v161
	v_mul_f32_e32 v161, v30, v161
	v_mul_f32_e32 v161, v171, v161
	v_cvt_pk_bf16_f32 v161, v161, s0
	v_cmp_gt_f32_e32 vcc, s93, v196
	global_store_short v[194:195], v161, off offset:96
	v_mul_f32_e32 v161, 0x4b800000, v196
	v_cndmask_b32_e32 v161, v196, v161, vcc
	v_rsq_f32_e32 v161, v161
	v_mul_f32_e32 v192, v170, v192
	v_cvt_pk_bf16_f32 v192, v192, s0
	global_store_short v[194:195], v192, off offset:64
	v_mul_f32_e32 v192, 0x45800000, v161
	v_cndmask_b32_e32 v161, v161, v192, vcc
	v_or_b32_e32 v194, 49, v160
	v_ashrrev_i32_e32 v195, 31, v194
	v_mul_f32_e32 v192, v115, v161
	v_lshlrev_b64 v[194:195], 12, v[194:195]
	v_mul_f32_e32 v192, v168, v192
	v_lshl_add_u64 v[194:195], v[158:159], 0, v[194:195]
	v_cvt_pk_bf16_f32 v192, v192, s0
	global_store_short v[194:195], v192, off
	v_mul_f32_e32 v192, v95, v161
	v_mul_f32_e32 v192, v169, v192
	v_cvt_pk_bf16_f32 v192, v192, s0
	global_store_short v[194:195], v192, off offset:32
	v_mul_f32_e32 v192, v59, v161
	v_mul_f32_e32 v161, v31, v161
	v_mul_f32_e32 v192, v170, v192
	v_mul_f32_e32 v161, v171, v161
	v_cvt_pk_bf16_f32 v192, v192, s0
	v_cvt_pk_bf16_f32 v161, v161, s0
	global_store_short v[194:195], v192, off offset:64
	global_store_short v[194:195], v161, off offset:96
	v_mov_b32_e32 v194, v116
	v_mov_b32_e32 v195, v96
	v_mov_b32_e32 v200, v117
	v_mov_b32_e32 v201, v97
	v_pk_mul_f32 v[194:195], v[194:195], v[194:195]
	v_mov_b32_e32 v196, v60
	v_mov_b32_e32 v197, v32
	v_pk_mul_f32 v[200:201], v[200:201], v[200:201]
	v_mov_b32_e32 v203, v33
	v_pk_mul_f32 v[196:197], v[196:197], v[196:197]
	v_pk_mul_f32 v[202:203], v[202:203], v[202:203]
	v_mov_b32_e32 v204, v200
	v_mov_b32_e32 v205, v194
	v_mov_b32_e32 v194, v201
	v_pk_add_f32 v[194:195], v[204:205], v[194:195]
	v_mov_b32_e32 v200, v202
	v_mov_b32_e32 v201, v196
	v_pk_add_f32 v[194:195], v[194:195], v[200:201]
	v_mov_b32_e32 v196, v203
	v_pk_add_f32 v[194:195], v[194:195], v[196:197]
	ds_bpermute_b32 v197, v175, v195
	ds_bpermute_b32 v196, v175, v194
	v_or_b32_e32 v198, 50, v160
	v_ashrrev_i32_e32 v199, 31, v198
	v_lshlrev_b64 v[198:199], 12, v[198:199]
	v_lshl_add_u64 v[198:199], v[158:159], 0, v[198:199]
	s_waitcnt lgkmcnt(0)
; __device__ __forceinline__ unsigned f2bf(float f) { const __bf16 b = (__bf16)f; return (unsigned)__builtin_bit_cast(unsigned short, b); }
;     __device__ __forceinline__ void operator()(Acc& acc, int pm, int pn, int wr, int wc, int fr, int fq) const {
;     ...
; #pragma unroll
;         for (int ai = 0; ai < 2; ++ai)
; #pragma unroll
;             for (int m = 0; m < 4; ++m)
; #pragma unroll
;                 for (int j = 0; j < 4; ++j) {
;                     float ss = acc[ai][0][m][0][j] * acc[ai][0][m][0][j] + acc[ai][0][m][1][j] * acc[ai][0][m][1][j] +
;                                acc[ai][1][m][0][j] * acc[ai][1][m][0][j] + acc[ai][1][m][1][j] * acc[ai][1][m][1][j];
;                     ss += __shfl_xor(ss, 1); ss += __shfl_xor(ss, 2); ss += __shfl_xor(ss, 4); ss += __shfl_xor(ss, 8);
;                     const float rs = rsqrtf(ss * (1.0f / 64.0f) + EPSV);
;                     bf16_t* rp = qk + (size_t)(pm * 256 + ai * 128 + wr * 64 + m * 16 + fq * 4 + j) * 2048 + head * 64 + fr;
; #pragma unroll
;                     for (int bj = 0; bj < 2; ++bj)
; #pragma unroll
;                         for (int n = 0; n < 2; ++n) rp[bj * 32 + n * 16] = (bf16_t)f2bf(acc[ai][bj][m][n][j] * rs * gv[bj][n]);
;                 }
	v_pk_add_f32 v[194:195], v[194:195], v[196:197]
	ds_bpermute_b32 v197, v174, v195
	ds_bpermute_b32 v196, v174, v194
	v_mov_b32_e32 v200, v99
	v_mov_b32_e32 v201, v71
	v_pk_mul_f32 v[200:201], v[200:201], v[200:201]
	v_mov_b32_e32 v202, v35
	s_waitcnt lgkmcnt(0)
	v_pk_add_f32 v[194:195], v[194:195], v[196:197]
	ds_bpermute_b32 v197, v173, v195
	ds_bpermute_b32 v196, v173, v194
	v_mov_b32_e32 v203, v15
	v_pk_mul_f32 v[202:203], v[202:203], v[202:203]
	v_mov_b32_e32 v204, v200
	v_mov_b32_e32 v200, v202
	s_waitcnt lgkmcnt(0)
	v_pk_add_f32 v[194:195], v[194:195], v[196:197]
	ds_bpermute_b32 v197, v172, v195
	ds_bpermute_b32 v196, v172, v194
	v_mov_b32_e32 v202, v37
	s_waitcnt lgkmcnt(0)
	v_pk_add_f32 v[194:195], v[194:195], v[196:197]
	s_nop 0
	v_pk_fma_f32 v[194:195], v[194:195], s[8:9], v[162:163] op_sel_hi:[1,0,0]
	v_mov_b32_e32 v196, v98
	v_mul_f32_e32 v161, 0x4b800000, v195
	v_cmp_gt_f32_e64 s[46:47], s93, v195
	v_mov_b32_e32 v197, v70
	v_pk_mul_f32 v[196:197], v[196:197], v[196:197]
	v_cndmask_b32_e64 v161, v195, v161, s[46:47]
	v_rsq_f32_e32 v161, v161
	v_mov_b32_e32 v205, v196
	v_mov_b32_e32 v196, v201
	v_pk_add_f32 v[196:197], v[204:205], v[196:197]
	v_mul_f32_e32 v192, 0x45800000, v161
	v_cndmask_b32_e64 v161, v161, v192, s[46:47]
	v_mul_f32_e32 v192, v116, v161
	v_mul_f32_e32 v192, v168, v192
	v_cvt_pk_bf16_f32 v192, v192, s0
	global_store_short v[198:199], v192, off
	v_mul_f32_e32 v192, v96, v161
	v_mul_f32_e32 v192, v169, v192
	v_cvt_pk_bf16_f32 v192, v192, s0
	global_store_short v[198:199], v192, off offset:32
	v_mul_f32_e32 v192, v60, v161
	v_mul_f32_e32 v161, v32, v161
	v_mul_f32_e32 v192, v170, v192
	v_mul_f32_e32 v161, v171, v161
	v_cvt_pk_bf16_f32 v192, v192, s0
	v_cvt_pk_bf16_f32 v161, v161, s0
	global_store_short v[198:199], v192, off offset:64
	global_store_short v[198:199], v161, off offset:96
	v_mov_b32_e32 v198, v34
	v_mov_b32_e32 v199, v14
	v_pk_mul_f32 v[198:199], v[198:199], v[198:199]
	v_cmp_gt_f32_e32 vcc, s93, v194
	v_mov_b32_e32 v201, v198
	v_pk_add_f32 v[196:197], v[196:197], v[200:201]
	v_mov_b32_e32 v198, v203
	v_pk_add_f32 v[196:197], v[196:197], v[198:199]
	ds_bpermute_b32 v199, v175, v197
	ds_bpermute_b32 v198, v175, v196
	v_mul_f32_e32 v161, 0x4b800000, v194
	v_cndmask_b32_e32 v161, v194, v161, vcc
	v_rsq_f32_e32 v161, v161
	v_or_b32_e32 v194, 51, v160
	s_waitcnt lgkmcnt(0)
	v_pk_add_f32 v[196:197], v[196:197], v[198:199]
	ds_bpermute_b32 v199, v174, v197
	ds_bpermute_b32 v198, v174, v196
	v_mul_f32_e32 v192, 0x45800000, v161
	v_cndmask_b32_e32 v161, v161, v192, vcc
	v_ashrrev_i32_e32 v195, 31, v194
	v_mul_f32_e32 v192, v117, v161
	s_waitcnt lgkmcnt(0)
	v_pk_add_f32 v[196:197], v[196:197], v[198:199]
	ds_bpermute_b32 v199, v173, v197
	ds_bpermute_b32 v198, v173, v196
	v_lshlrev_b64 v[194:195], 12, v[194:195]
	v_mul_f32_e32 v192, v168, v192
	v_lshl_add_u64 v[194:195], v[158:159], 0, v[194:195]
	v_cvt_pk_bf16_f32 v192, v192, s0
	s_waitcnt lgkmcnt(0)
	v_pk_add_f32 v[196:197], v[196:197], v[198:199]
	ds_bpermute_b32 v199, v172, v197
	ds_bpermute_b32 v198, v172, v196
	global_store_short v[194:195], v192, off
	v_mul_f32_e32 v192, v97, v161
	v_mul_f32_e32 v192, v169, v192
	v_cvt_pk_bf16_f32 v192, v192, s0
	global_store_short v[194:195], v192, off offset:32
	v_mul_f32_e32 v192, v61, v161
	v_mul_f32_e32 v161, v33, v161
	v_mul_f32_e32 v161, v171, v161
	s_waitcnt lgkmcnt(0)
	v_pk_add_f32 v[196:197], v[196:197], v[198:199]
	v_cvt_pk_bf16_f32 v161, v161, s0
	v_pk_fma_f32 v[196:197], v[196:197], s[8:9], v[162:163] op_sel_hi:[1,0,0]
	global_store_short v[194:195], v161, off offset:96
	v_mul_f32_e32 v161, 0x4b800000, v197
	v_cmp_gt_f32_e64 s[46:47], s93, v197
	v_mul_f32_e32 v192, v170, v192
	v_cvt_pk_bf16_f32 v192, v192, s0
	v_cndmask_b32_e64 v161, v197, v161, s[46:47]
	v_rsq_f32_e32 v161, v161
	global_store_short v[194:195], v192, off offset:64
	v_add_u32_e32 v194, 0x80, v160
	v_ashrrev_i32_e32 v195, 31, v194
	v_mul_f32_e32 v192, 0x45800000, v161
	v_cndmask_b32_e64 v161, v161, v192, s[46:47]
	v_mul_f32_e32 v192, v98, v161
	v_lshlrev_b64 v[194:195], 12, v[194:195]
	v_mul_f32_e32 v192, v168, v192
	v_lshl_add_u64 v[194:195], v[158:159], 0, v[194:195]
	v_cvt_pk_bf16_f32 v192, v192, s0
	global_store_short v[194:195], v192, off
	v_mul_f32_e32 v192, v70, v161
	v_mul_f32_e32 v192, v169, v192
	v_cvt_pk_bf16_f32 v192, v192, s0
	global_store_short v[194:195], v192, off offset:32
	v_mul_f32_e32 v192, v34, v161
	v_mul_f32_e32 v161, v14, v161
	v_mul_f32_e32 v161, v171, v161
	v_cvt_pk_bf16_f32 v161, v161, s0
	v_cmp_gt_f32_e32 vcc, s93, v196
	global_store_short v[194:195], v161, off offset:96
	v_mul_f32_e32 v161, 0x4b800000, v196
	v_cndmask_b32_e32 v161, v196, v161, vcc
	v_rsq_f32_e32 v161, v161
	v_mul_f32_e32 v192, v170, v192
	v_cvt_pk_bf16_f32 v192, v192, s0
	global_store_short v[194:195], v192, off offset:64
	v_mul_f32_e32 v192, 0x45800000, v161
	v_cndmask_b32_e32 v161, v161, v192, vcc
	v_add_u32_e32 v194, 0x81, v160
	v_ashrrev_i32_e32 v195, 31, v194
	v_mul_f32_e32 v192, v99, v161
	v_lshlrev_b64 v[194:195], 12, v[194:195]
	v_mul_f32_e32 v192, v168, v192
	v_lshl_add_u64 v[194:195], v[158:159], 0, v[194:195]
	v_cvt_pk_bf16_f32 v192, v192, s0
	global_store_short v[194:195], v192, off
	v_mul_f32_e32 v192, v71, v161
	v_mul_f32_e32 v192, v169, v192
	v_cvt_pk_bf16_f32 v192, v192, s0
	global_store_short v[194:195], v192, off offset:32
	v_mul_f32_e32 v192, v35, v161
	v_mul_f32_e32 v161, v15, v161
	v_mul_f32_e32 v192, v170, v192
	v_mul_f32_e32 v161, v171, v161
	v_cvt_pk_bf16_f32 v192, v192, s0
	v_cvt_pk_bf16_f32 v161, v161, s0
	global_store_short v[194:195], v192, off offset:64
	global_store_short v[194:195], v161, off offset:96
	v_mov_b32_e32 v194, v100
	v_mov_b32_e32 v195, v72
	v_mov_b32_e32 v200, v101
	v_mov_b32_e32 v201, v73
	v_pk_mul_f32 v[194:195], v[194:195], v[194:195]
	v_mov_b32_e32 v196, v36
	v_mov_b32_e32 v197, v16
	v_pk_mul_f32 v[200:201], v[200:201], v[200:201]
	v_mov_b32_e32 v203, v17
	v_pk_mul_f32 v[196:197], v[196:197], v[196:197]
	v_pk_mul_f32 v[202:203], v[202:203], v[202:203]
	v_mov_b32_e32 v204, v200
	v_mov_b32_e32 v205, v194
	v_mov_b32_e32 v194, v201
	v_pk_add_f32 v[194:195], v[204:205], v[194:195]
	v_mov_b32_e32 v200, v202
	v_mov_b32_e32 v201, v196
	v_pk_add_f32 v[194:195], v[194:195], v[200:201]
	v_mov_b32_e32 v196, v203
	v_pk_add_f32 v[194:195], v[194:195], v[196:197]
	ds_bpermute_b32 v197, v175, v195
	ds_bpermute_b32 v196, v175, v194
	v_add_u32_e32 v198, 0x82, v160
	v_ashrrev_i32_e32 v199, 31, v198
	v_lshlrev_b64 v[198:199], 12, v[198:199]
	v_lshl_add_u64 v[198:199], v[158:159], 0, v[198:199]
	s_waitcnt lgkmcnt(0)
; __device__ __forceinline__ unsigned f2bf(float f) { const __bf16 b = (__bf16)f; return (unsigned)__builtin_bit_cast(unsigned short, b); }
;     __device__ __forceinline__ void operator()(Acc& acc, int pm, int pn, int wr, int wc, int fr, int fq) const {
;     ...
; #pragma unroll
;         for (int ai = 0; ai < 2; ++ai)
; #pragma unroll
;             for (int m = 0; m < 4; ++m)
; #pragma unroll
;                 for (int j = 0; j < 4; ++j) {
;                     float ss = acc[ai][0][m][0][j] * acc[ai][0][m][0][j] + acc[ai][0][m][1][j] * acc[ai][0][m][1][j] +
;                                acc[ai][1][m][0][j] * acc[ai][1][m][0][j] + acc[ai][1][m][1][j] * acc[ai][1][m][1][j];
;                     ss += __shfl_xor(ss, 1); ss += __shfl_xor(ss, 2); ss += __shfl_xor(ss, 4); ss += __shfl_xor(ss, 8);
;                     const float rs = rsqrtf(ss * (1.0f / 64.0f) + EPSV);
;                     bf16_t* rp = qk + (size_t)(pm * 256 + ai * 128 + wr * 64 + m * 16 + fq * 4 + j) * 2048 + head * 64 + fr;
; #pragma unroll
;                     for (int bj = 0; bj < 2; ++bj)
; #pragma unroll
;                         for (int n = 0; n < 2; ++n) rp[bj * 32 + n * 16] = (bf16_t)f2bf(acc[ai][bj][m][n][j] * rs * gv[bj][n]);
;                 }
	v_pk_add_f32 v[194:195], v[194:195], v[196:197]
	ds_bpermute_b32 v197, v174, v195
	ds_bpermute_b32 v196, v174, v194
	v_mov_b32_e32 v200, v91
	v_mov_b32_e32 v201, v63
	v_pk_mul_f32 v[200:201], v[200:201], v[200:201]
	v_mov_b32_e32 v202, v27
	s_waitcnt lgkmcnt(0)
	v_pk_add_f32 v[194:195], v[194:195], v[196:197]
	ds_bpermute_b32 v197, v173, v195
	ds_bpermute_b32 v196, v173, v194
	v_mov_b32_e32 v203, v11
	v_pk_mul_f32 v[202:203], v[202:203], v[202:203]
	v_mov_b32_e32 v204, v200
	v_mov_b32_e32 v200, v202
	s_waitcnt lgkmcnt(0)
	v_pk_add_f32 v[194:195], v[194:195], v[196:197]
	ds_bpermute_b32 v197, v172, v195
	ds_bpermute_b32 v196, v172, v194
	v_mov_b32_e32 v202, v29
	s_waitcnt lgkmcnt(0)
	v_pk_add_f32 v[194:195], v[194:195], v[196:197]
	s_nop 0
	v_pk_fma_f32 v[194:195], v[194:195], s[8:9], v[162:163] op_sel_hi:[1,0,0]
	v_mov_b32_e32 v196, v90
	v_mul_f32_e32 v161, 0x4b800000, v195
	v_cmp_gt_f32_e64 s[46:47], s93, v195
	v_mov_b32_e32 v197, v62
	v_pk_mul_f32 v[196:197], v[196:197], v[196:197]
	v_cndmask_b32_e64 v161, v195, v161, s[46:47]
	v_rsq_f32_e32 v161, v161
	v_mov_b32_e32 v205, v196
	v_mov_b32_e32 v196, v201
	v_pk_add_f32 v[196:197], v[204:205], v[196:197]
	v_mul_f32_e32 v192, 0x45800000, v161
	v_cndmask_b32_e64 v161, v161, v192, s[46:47]
	v_mul_f32_e32 v192, v100, v161
	v_mul_f32_e32 v192, v168, v192
	v_cvt_pk_bf16_f32 v192, v192, s0
	global_store_short v[198:199], v192, off
	v_mul_f32_e32 v192, v72, v161
	v_mul_f32_e32 v192, v169, v192
	v_cvt_pk_bf16_f32 v192, v192, s0
	global_store_short v[198:199], v192, off offset:32
	v_mul_f32_e32 v192, v36, v161
	v_mul_f32_e32 v161, v16, v161
	v_mul_f32_e32 v192, v170, v192
	v_mul_f32_e32 v161, v171, v161
	v_cvt_pk_bf16_f32 v192, v192, s0
	v_cvt_pk_bf16_f32 v161, v161, s0
	global_store_short v[198:199], v192, off offset:64
	global_store_short v[198:199], v161, off offset:96
	v_mov_b32_e32 v198, v26
	v_mov_b32_e32 v199, v10
	v_pk_mul_f32 v[198:199], v[198:199], v[198:199]
	v_cmp_gt_f32_e32 vcc, s93, v194
	v_mov_b32_e32 v201, v198
	v_pk_add_f32 v[196:197], v[196:197], v[200:201]
	v_mov_b32_e32 v198, v203
	v_pk_add_f32 v[196:197], v[196:197], v[198:199]
	ds_bpermute_b32 v199, v175, v197
	ds_bpermute_b32 v198, v175, v196
	v_mul_f32_e32 v161, 0x4b800000, v194
	v_cndmask_b32_e32 v161, v194, v161, vcc
	v_rsq_f32_e32 v161, v161
	v_add_u32_e32 v194, 0x83, v160
	s_waitcnt lgkmcnt(0)
	v_pk_add_f32 v[196:197], v[196:197], v[198:199]
	ds_bpermute_b32 v199, v174, v197
	ds_bpermute_b32 v198, v174, v196
	v_mul_f32_e32 v192, 0x45800000, v161
	v_cndmask_b32_e32 v161, v161, v192, vcc
	v_ashrrev_i32_e32 v195, 31, v194
	v_mul_f32_e32 v192, v101, v161
	s_waitcnt lgkmcnt(0)
	v_pk_add_f32 v[196:197], v[196:197], v[198:199]
	ds_bpermute_b32 v199, v173, v197
	ds_bpermute_b32 v198, v173, v196
	v_lshlrev_b64 v[194:195], 12, v[194:195]
	v_mul_f32_e32 v192, v168, v192
	v_lshl_add_u64 v[194:195], v[158:159], 0, v[194:195]
	v_cvt_pk_bf16_f32 v192, v192, s0
	s_waitcnt lgkmcnt(0)
	v_pk_add_f32 v[196:197], v[196:197], v[198:199]
	ds_bpermute_b32 v199, v172, v197
	ds_bpermute_b32 v198, v172, v196
	global_store_short v[194:195], v192, off
	v_mul_f32_e32 v192, v73, v161
	v_mul_f32_e32 v192, v169, v192
	v_cvt_pk_bf16_f32 v192, v192, s0
	global_store_short v[194:195], v192, off offset:32
	v_mul_f32_e32 v192, v37, v161
	v_mul_f32_e32 v161, v17, v161
	v_mul_f32_e32 v161, v171, v161
	s_waitcnt lgkmcnt(0)
	v_pk_add_f32 v[196:197], v[196:197], v[198:199]
	v_cvt_pk_bf16_f32 v161, v161, s0
	v_pk_fma_f32 v[196:197], v[196:197], s[8:9], v[162:163] op_sel_hi:[1,0,0]
	global_store_short v[194:195], v161, off offset:96
	v_mul_f32_e32 v161, 0x4b800000, v197
	v_cmp_gt_f32_e64 s[46:47], s93, v197
	v_mul_f32_e32 v192, v170, v192
	v_cvt_pk_bf16_f32 v192, v192, s0
	v_cndmask_b32_e64 v161, v197, v161, s[46:47]
	v_rsq_f32_e32 v161, v161
	global_store_short v[194:195], v192, off offset:64
	v_add_u32_e32 v194, 0x90, v160
	v_ashrrev_i32_e32 v195, 31, v194
	v_mul_f32_e32 v192, 0x45800000, v161
	v_cndmask_b32_e64 v161, v161, v192, s[46:47]
	v_mul_f32_e32 v192, v90, v161
	v_lshlrev_b64 v[194:195], 12, v[194:195]
	v_mul_f32_e32 v192, v168, v192
	v_lshl_add_u64 v[194:195], v[158:159], 0, v[194:195]
	v_cvt_pk_bf16_f32 v192, v192, s0
	global_store_short v[194:195], v192, off
	v_mul_f32_e32 v192, v62, v161
	v_mul_f32_e32 v192, v169, v192
	v_cvt_pk_bf16_f32 v192, v192, s0
	global_store_short v[194:195], v192, off offset:32
	v_mul_f32_e32 v192, v26, v161
	v_mul_f32_e32 v161, v10, v161
	v_mul_f32_e32 v161, v171, v161
	v_cvt_pk_bf16_f32 v161, v161, s0
	v_cmp_gt_f32_e32 vcc, s93, v196
	global_store_short v[194:195], v161, off offset:96
	v_mul_f32_e32 v161, 0x4b800000, v196
	v_cndmask_b32_e32 v161, v196, v161, vcc
	v_rsq_f32_e32 v161, v161
	v_mul_f32_e32 v192, v170, v192
	v_cvt_pk_bf16_f32 v192, v192, s0
	global_store_short v[194:195], v192, off offset:64
	v_mul_f32_e32 v192, 0x45800000, v161
	v_cndmask_b32_e32 v161, v161, v192, vcc
	v_add_u32_e32 v194, 0x91, v160
	v_ashrrev_i32_e32 v195, 31, v194
	v_mul_f32_e32 v192, v91, v161
	v_lshlrev_b64 v[194:195], 12, v[194:195]
	v_mul_f32_e32 v192, v168, v192
	v_lshl_add_u64 v[194:195], v[158:159], 0, v[194:195]
	v_cvt_pk_bf16_f32 v192, v192, s0
	global_store_short v[194:195], v192, off
	v_mul_f32_e32 v192, v63, v161
	v_mul_f32_e32 v192, v169, v192
	v_cvt_pk_bf16_f32 v192, v192, s0
	global_store_short v[194:195], v192, off offset:32
	v_mul_f32_e32 v192, v27, v161
	v_mul_f32_e32 v161, v11, v161
	v_mul_f32_e32 v192, v170, v192
	v_mul_f32_e32 v161, v171, v161
	v_cvt_pk_bf16_f32 v192, v192, s0
	v_cvt_pk_bf16_f32 v161, v161, s0
	global_store_short v[194:195], v192, off offset:64
	global_store_short v[194:195], v161, off offset:96
	v_mov_b32_e32 v194, v92
	v_mov_b32_e32 v195, v64
	v_mov_b32_e32 v200, v93
	v_mov_b32_e32 v201, v65
	v_pk_mul_f32 v[194:195], v[194:195], v[194:195]
	v_mov_b32_e32 v196, v28
	v_mov_b32_e32 v197, v12
	v_pk_mul_f32 v[200:201], v[200:201], v[200:201]
	v_mov_b32_e32 v203, v13
	v_pk_mul_f32 v[196:197], v[196:197], v[196:197]
	v_pk_mul_f32 v[202:203], v[202:203], v[202:203]
	v_mov_b32_e32 v204, v200
	v_mov_b32_e32 v205, v194
	v_mov_b32_e32 v194, v201
	v_pk_add_f32 v[194:195], v[204:205], v[194:195]
	v_mov_b32_e32 v200, v202
	v_mov_b32_e32 v201, v196
	v_pk_add_f32 v[194:195], v[194:195], v[200:201]
	v_mov_b32_e32 v196, v203
	v_pk_add_f32 v[194:195], v[194:195], v[196:197]
	ds_bpermute_b32 v197, v175, v195
	ds_bpermute_b32 v196, v175, v194
	v_add_u32_e32 v198, 0x92, v160
	v_ashrrev_i32_e32 v199, 31, v198
	v_lshlrev_b64 v[198:199], 12, v[198:199]
	v_lshl_add_u64 v[198:199], v[158:159], 0, v[198:199]
	s_waitcnt lgkmcnt(0)
; __device__ __forceinline__ unsigned f2bf(float f) { const __bf16 b = (__bf16)f; return (unsigned)__builtin_bit_cast(unsigned short, b); }
;     __device__ __forceinline__ void operator()(Acc& acc, int pm, int pn, int wr, int wc, int fr, int fq) const {
;     ...
; #pragma unroll
;         for (int ai = 0; ai < 2; ++ai)
; #pragma unroll
;             for (int m = 0; m < 4; ++m)
; #pragma unroll
;                 for (int j = 0; j < 4; ++j) {
;                     float ss = acc[ai][0][m][0][j] * acc[ai][0][m][0][j] + acc[ai][0][m][1][j] * acc[ai][0][m][1][j] +
;                                acc[ai][1][m][0][j] * acc[ai][1][m][0][j] + acc[ai][1][m][1][j] * acc[ai][1][m][1][j];
;                     ss += __shfl_xor(ss, 1); ss += __shfl_xor(ss, 2); ss += __shfl_xor(ss, 4); ss += __shfl_xor(ss, 8);
;                     const float rs = rsqrtf(ss * (1.0f / 64.0f) + EPSV);
;                     bf16_t* rp = qk + (size_t)(pm * 256 + ai * 128 + wr * 64 + m * 16 + fq * 4 + j) * 2048 + head * 64 + fr;
; #pragma unroll
;                     for (int bj = 0; bj < 2; ++bj)
; #pragma unroll
;                         for (int n = 0; n < 2; ++n) rp[bj * 32 + n * 16] = (bf16_t)f2bf(acc[ai][bj][m][n][j] * rs * gv[bj][n]);
;                 }
	v_pk_add_f32 v[194:195], v[194:195], v[196:197]
	ds_bpermute_b32 v197, v174, v195
	ds_bpermute_b32 v196, v174, v194
	v_mov_b32_e32 v200, v87
	v_mov_b32_e32 v201, v55
	v_pk_mul_f32 v[200:201], v[200:201], v[200:201]
	v_mov_b32_e32 v202, v23
	s_waitcnt lgkmcnt(0)
	v_pk_add_f32 v[194:195], v[194:195], v[196:197]
	ds_bpermute_b32 v197, v173, v195
	ds_bpermute_b32 v196, v173, v194
	v_mov_b32_e32 v203, v7
	v_pk_mul_f32 v[202:203], v[202:203], v[202:203]
	v_mov_b32_e32 v204, v200
	v_mov_b32_e32 v200, v202
	s_waitcnt lgkmcnt(0)
	v_pk_add_f32 v[194:195], v[194:195], v[196:197]
	ds_bpermute_b32 v197, v172, v195
	ds_bpermute_b32 v196, v172, v194
	v_mov_b32_e32 v202, v25
	s_waitcnt lgkmcnt(0)
	v_pk_add_f32 v[194:195], v[194:195], v[196:197]
	s_nop 0
	v_pk_fma_f32 v[194:195], v[194:195], s[8:9], v[162:163] op_sel_hi:[1,0,0]
	v_mov_b32_e32 v196, v86
	v_mul_f32_e32 v161, 0x4b800000, v195
	v_cmp_gt_f32_e64 s[46:47], s93, v195
	v_mov_b32_e32 v197, v54
	v_pk_mul_f32 v[196:197], v[196:197], v[196:197]
	v_cndmask_b32_e64 v161, v195, v161, s[46:47]
	v_rsq_f32_e32 v161, v161
	v_mov_b32_e32 v205, v196
	v_mov_b32_e32 v196, v201
	v_pk_add_f32 v[196:197], v[204:205], v[196:197]
	v_mul_f32_e32 v192, 0x45800000, v161
	v_cndmask_b32_e64 v161, v161, v192, s[46:47]
	v_mul_f32_e32 v192, v92, v161
	v_mul_f32_e32 v192, v168, v192
	v_cvt_pk_bf16_f32 v192, v192, s0
	global_store_short v[198:199], v192, off
	v_mul_f32_e32 v192, v64, v161
	v_mul_f32_e32 v192, v169, v192
	v_cvt_pk_bf16_f32 v192, v192, s0
	global_store_short v[198:199], v192, off offset:32
	v_mul_f32_e32 v192, v28, v161
	v_mul_f32_e32 v161, v12, v161
	v_mul_f32_e32 v192, v170, v192
	v_mul_f32_e32 v161, v171, v161
	v_cvt_pk_bf16_f32 v192, v192, s0
	v_cvt_pk_bf16_f32 v161, v161, s0
	global_store_short v[198:199], v192, off offset:64
	global_store_short v[198:199], v161, off offset:96
	v_mov_b32_e32 v198, v22
	v_mov_b32_e32 v199, v6
	v_pk_mul_f32 v[198:199], v[198:199], v[198:199]
	v_cmp_gt_f32_e32 vcc, s93, v194
	v_mov_b32_e32 v201, v198
	v_pk_add_f32 v[196:197], v[196:197], v[200:201]
	v_mov_b32_e32 v198, v203
	v_pk_add_f32 v[196:197], v[196:197], v[198:199]
	ds_bpermute_b32 v199, v175, v197
	ds_bpermute_b32 v198, v175, v196
	v_mul_f32_e32 v161, 0x4b800000, v194
	v_cndmask_b32_e32 v161, v194, v161, vcc
	v_rsq_f32_e32 v161, v161
	v_add_u32_e32 v194, 0x93, v160
	s_waitcnt lgkmcnt(0)
	v_pk_add_f32 v[196:197], v[196:197], v[198:199]
	ds_bpermute_b32 v199, v174, v197
	ds_bpermute_b32 v198, v174, v196
	v_mul_f32_e32 v192, 0x45800000, v161
	v_cndmask_b32_e32 v161, v161, v192, vcc
	v_ashrrev_i32_e32 v195, 31, v194
	v_mul_f32_e32 v192, v93, v161
	s_waitcnt lgkmcnt(0)
	v_pk_add_f32 v[196:197], v[196:197], v[198:199]
	ds_bpermute_b32 v199, v173, v197
	ds_bpermute_b32 v198, v173, v196
	v_lshlrev_b64 v[194:195], 12, v[194:195]
	v_mul_f32_e32 v192, v168, v192
	v_lshl_add_u64 v[194:195], v[158:159], 0, v[194:195]
	v_cvt_pk_bf16_f32 v192, v192, s0
	s_waitcnt lgkmcnt(0)
	v_pk_add_f32 v[196:197], v[196:197], v[198:199]
	ds_bpermute_b32 v199, v172, v197
	ds_bpermute_b32 v198, v172, v196
	global_store_short v[194:195], v192, off
	v_mul_f32_e32 v192, v65, v161
	v_mul_f32_e32 v192, v169, v192
	v_cvt_pk_bf16_f32 v192, v192, s0
	global_store_short v[194:195], v192, off offset:32
	v_mul_f32_e32 v192, v29, v161
	v_mul_f32_e32 v161, v13, v161
	v_mul_f32_e32 v161, v171, v161
	s_waitcnt lgkmcnt(0)
	v_pk_add_f32 v[196:197], v[196:197], v[198:199]
	v_cvt_pk_bf16_f32 v161, v161, s0
	v_pk_fma_f32 v[196:197], v[196:197], s[8:9], v[162:163] op_sel_hi:[1,0,0]
	global_store_short v[194:195], v161, off offset:96
	v_mul_f32_e32 v161, 0x4b800000, v197
	v_cmp_gt_f32_e64 s[46:47], s93, v197
	v_mul_f32_e32 v192, v170, v192
	v_cvt_pk_bf16_f32 v192, v192, s0
	v_cndmask_b32_e64 v161, v197, v161, s[46:47]
	v_rsq_f32_e32 v161, v161
	global_store_short v[194:195], v192, off offset:64
	v_add_u32_e32 v194, 0xa0, v160
	v_ashrrev_i32_e32 v195, 31, v194
	v_mul_f32_e32 v192, 0x45800000, v161
	v_cndmask_b32_e64 v161, v161, v192, s[46:47]
	v_mul_f32_e32 v192, v86, v161
	v_lshlrev_b64 v[194:195], 12, v[194:195]
	v_mul_f32_e32 v192, v168, v192
	v_lshl_add_u64 v[194:195], v[158:159], 0, v[194:195]
	v_cvt_pk_bf16_f32 v192, v192, s0
	global_store_short v[194:195], v192, off
	v_mul_f32_e32 v192, v54, v161
	v_mul_f32_e32 v192, v169, v192
	v_cvt_pk_bf16_f32 v192, v192, s0
	global_store_short v[194:195], v192, off offset:32
	v_mul_f32_e32 v192, v22, v161
	v_mul_f32_e32 v161, v6, v161
	v_mul_f32_e32 v161, v171, v161
	v_cvt_pk_bf16_f32 v161, v161, s0
	v_cmp_gt_f32_e32 vcc, s93, v196
	global_store_short v[194:195], v161, off offset:96
	v_mul_f32_e32 v161, 0x4b800000, v196
	v_cndmask_b32_e32 v161, v196, v161, vcc
	v_rsq_f32_e32 v161, v161
	v_mul_f32_e32 v192, v170, v192
	v_cvt_pk_bf16_f32 v192, v192, s0
	global_store_short v[194:195], v192, off offset:64
	v_mul_f32_e32 v192, 0x45800000, v161
	v_cndmask_b32_e32 v161, v161, v192, vcc
	v_add_u32_e32 v194, 0xa1, v160
	v_ashrrev_i32_e32 v195, 31, v194
	v_mul_f32_e32 v192, v87, v161
	v_lshlrev_b64 v[194:195], 12, v[194:195]
	v_mul_f32_e32 v192, v168, v192
	v_lshl_add_u64 v[194:195], v[158:159], 0, v[194:195]
	v_cvt_pk_bf16_f32 v192, v192, s0
	global_store_short v[194:195], v192, off
	v_mul_f32_e32 v192, v55, v161
	v_mul_f32_e32 v192, v169, v192
	v_cvt_pk_bf16_f32 v192, v192, s0
	global_store_short v[194:195], v192, off offset:32
	v_mul_f32_e32 v192, v23, v161
	v_mul_f32_e32 v161, v7, v161
	v_mul_f32_e32 v192, v170, v192
	v_mul_f32_e32 v161, v171, v161
	v_cvt_pk_bf16_f32 v192, v192, s0
	v_cvt_pk_bf16_f32 v161, v161, s0
	global_store_short v[194:195], v192, off offset:64
	global_store_short v[194:195], v161, off offset:96
	v_mov_b32_e32 v194, v88
	v_mov_b32_e32 v195, v56
	v_mov_b32_e32 v200, v89
	v_mov_b32_e32 v201, v57
	v_pk_mul_f32 v[194:195], v[194:195], v[194:195]
	v_mov_b32_e32 v196, v24
	v_mov_b32_e32 v197, v8
	v_pk_mul_f32 v[200:201], v[200:201], v[200:201]
	v_mov_b32_e32 v203, v9
	v_pk_mul_f32 v[196:197], v[196:197], v[196:197]
	v_pk_mul_f32 v[202:203], v[202:203], v[202:203]
	v_mov_b32_e32 v204, v200
	v_mov_b32_e32 v205, v194
	v_mov_b32_e32 v194, v201
	v_pk_add_f32 v[194:195], v[204:205], v[194:195]
	v_mov_b32_e32 v200, v202
	v_mov_b32_e32 v201, v196
	v_pk_add_f32 v[194:195], v[194:195], v[200:201]
	v_mov_b32_e32 v196, v203
	v_pk_add_f32 v[194:195], v[194:195], v[196:197]
	ds_bpermute_b32 v197, v175, v195
	ds_bpermute_b32 v196, v175, v194
	v_add_u32_e32 v198, 0xa2, v160
	v_ashrrev_i32_e32 v199, 31, v198
	v_lshlrev_b64 v[198:199], 12, v[198:199]
	v_lshl_add_u64 v[198:199], v[158:159], 0, v[198:199]
	s_waitcnt lgkmcnt(0)
; __device__ __forceinline__ unsigned f2bf(float f) { const __bf16 b = (__bf16)f; return (unsigned)__builtin_bit_cast(unsigned short, b); }
;     __device__ __forceinline__ void operator()(Acc& acc, int pm, int pn, int wr, int wc, int fr, int fq) const {
;     ...
; #pragma unroll
;         for (int ai = 0; ai < 2; ++ai)
; #pragma unroll
;             for (int m = 0; m < 4; ++m)
; #pragma unroll
;                 for (int j = 0; j < 4; ++j) {
;                     float ss = acc[ai][0][m][0][j] * acc[ai][0][m][0][j] + acc[ai][0][m][1][j] * acc[ai][0][m][1][j] +
;                                acc[ai][1][m][0][j] * acc[ai][1][m][0][j] + acc[ai][1][m][1][j] * acc[ai][1][m][1][j];
;                     ss += __shfl_xor(ss, 1); ss += __shfl_xor(ss, 2); ss += __shfl_xor(ss, 4); ss += __shfl_xor(ss, 8);
;                     const float rs = rsqrtf(ss * (1.0f / 64.0f) + EPSV);
;                     bf16_t* rp = qk + (size_t)(pm * 256 + ai * 128 + wr * 64 + m * 16 + fq * 4 + j) * 2048 + head * 64 + fr;
; #pragma unroll
;                     for (int bj = 0; bj < 2; ++bj)
; #pragma unroll
;                         for (int n = 0; n < 2; ++n) rp[bj * 32 + n * 16] = (bf16_t)f2bf(acc[ai][bj][m][n][j] * rs * gv[bj][n]);
;                 }
	v_pk_add_f32 v[194:195], v[194:195], v[196:197]
	ds_bpermute_b32 v197, v174, v195
	ds_bpermute_b32 v196, v174, v194
	v_mov_b32_e32 v200, v79
	v_mov_b32_e32 v201, v47
	v_pk_mul_f32 v[200:201], v[200:201], v[200:201]
	v_mov_b32_e32 v202, v19
	s_waitcnt lgkmcnt(0)
	v_pk_add_f32 v[194:195], v[194:195], v[196:197]
	ds_bpermute_b32 v197, v173, v195
	ds_bpermute_b32 v196, v173, v194
	v_mov_b32_e32 v203, v3
	v_pk_mul_f32 v[202:203], v[202:203], v[202:203]
	v_mov_b32_e32 v204, v200
	v_mov_b32_e32 v200, v202
	s_waitcnt lgkmcnt(0)
	v_pk_add_f32 v[194:195], v[194:195], v[196:197]
	ds_bpermute_b32 v197, v172, v195
	ds_bpermute_b32 v196, v172, v194
	v_mov_b32_e32 v202, v21
	s_waitcnt lgkmcnt(0)
	v_pk_add_f32 v[194:195], v[194:195], v[196:197]
	s_nop 0
	v_pk_fma_f32 v[194:195], v[194:195], s[8:9], v[162:163] op_sel_hi:[1,0,0]
	v_mov_b32_e32 v196, v78
	v_mul_f32_e32 v161, 0x4b800000, v195
	v_cmp_gt_f32_e64 s[46:47], s93, v195
	v_mov_b32_e32 v197, v46
	v_pk_mul_f32 v[196:197], v[196:197], v[196:197]
	v_cndmask_b32_e64 v161, v195, v161, s[46:47]
	v_rsq_f32_e32 v161, v161
	v_mov_b32_e32 v205, v196
	v_mov_b32_e32 v196, v201
	v_pk_add_f32 v[196:197], v[204:205], v[196:197]
	v_mul_f32_e32 v192, 0x45800000, v161
	v_cndmask_b32_e64 v161, v161, v192, s[46:47]
	v_mul_f32_e32 v192, v88, v161
	v_mul_f32_e32 v192, v168, v192
	v_cvt_pk_bf16_f32 v192, v192, s0
	global_store_short v[198:199], v192, off
	v_mul_f32_e32 v192, v56, v161
	v_mul_f32_e32 v192, v169, v192
	v_cvt_pk_bf16_f32 v192, v192, s0
	global_store_short v[198:199], v192, off offset:32
	v_mul_f32_e32 v192, v24, v161
	v_mul_f32_e32 v161, v8, v161
	v_mul_f32_e32 v192, v170, v192
	v_mul_f32_e32 v161, v171, v161
	v_cvt_pk_bf16_f32 v192, v192, s0
	v_cvt_pk_bf16_f32 v161, v161, s0
	global_store_short v[198:199], v192, off offset:64
	global_store_short v[198:199], v161, off offset:96
	v_mov_b32_e32 v198, v18
	v_mov_b32_e32 v199, v2
	v_pk_mul_f32 v[198:199], v[198:199], v[198:199]
	v_cmp_gt_f32_e32 vcc, s93, v194
	v_mov_b32_e32 v201, v198
	v_pk_add_f32 v[196:197], v[196:197], v[200:201]
	v_mov_b32_e32 v198, v203
	v_pk_add_f32 v[196:197], v[196:197], v[198:199]
	ds_bpermute_b32 v199, v175, v197
	ds_bpermute_b32 v198, v175, v196
	v_mul_f32_e32 v161, 0x4b800000, v194
	v_cndmask_b32_e32 v161, v194, v161, vcc
	v_rsq_f32_e32 v161, v161
	v_add_u32_e32 v194, 0xa3, v160
	s_waitcnt lgkmcnt(0)
	v_pk_add_f32 v[196:197], v[196:197], v[198:199]
	ds_bpermute_b32 v199, v174, v197
	ds_bpermute_b32 v198, v174, v196
	v_mul_f32_e32 v192, 0x45800000, v161
	v_cndmask_b32_e32 v161, v161, v192, vcc
	v_ashrrev_i32_e32 v195, 31, v194
	v_mul_f32_e32 v192, v89, v161
	s_waitcnt lgkmcnt(0)
	v_pk_add_f32 v[196:197], v[196:197], v[198:199]
	ds_bpermute_b32 v199, v173, v197
	ds_bpermute_b32 v198, v173, v196
	v_lshlrev_b64 v[194:195], 12, v[194:195]
	v_mul_f32_e32 v192, v168, v192
	v_lshl_add_u64 v[194:195], v[158:159], 0, v[194:195]
	v_cvt_pk_bf16_f32 v192, v192, s0
	s_waitcnt lgkmcnt(0)
	v_pk_add_f32 v[196:197], v[196:197], v[198:199]
	ds_bpermute_b32 v199, v172, v197
	ds_bpermute_b32 v198, v172, v196
	global_store_short v[194:195], v192, off
	v_mul_f32_e32 v192, v57, v161
	v_mul_f32_e32 v192, v169, v192
	v_cvt_pk_bf16_f32 v192, v192, s0
	global_store_short v[194:195], v192, off offset:32
	v_mul_f32_e32 v192, v25, v161
	v_mul_f32_e32 v161, v9, v161
	v_mul_f32_e32 v161, v171, v161
	s_waitcnt lgkmcnt(0)
; __device__ __forceinline__ unsigned f2bf(float f) { const __bf16 b = (__bf16)f; return (unsigned)__builtin_bit_cast(unsigned short, b); }
;     __device__ __forceinline__ void operator()(Acc& acc, int pm, int pn, int wr, int wc, int fr, int fq) const {
;     ...
; #pragma unroll
;         for (int ai = 0; ai < 2; ++ai)
; #pragma unroll
;             for (int m = 0; m < 4; ++m)
; #pragma unroll
;                 for (int j = 0; j < 4; ++j) {
;                     float ss = acc[ai][0][m][0][j] * acc[ai][0][m][0][j] + acc[ai][0][m][1][j] * acc[ai][0][m][1][j] +
;                                acc[ai][1][m][0][j] * acc[ai][1][m][0][j] + acc[ai][1][m][1][j] * acc[ai][1][m][1][j];
;                     ss += __shfl_xor(ss, 1); ss += __shfl_xor(ss, 2); ss += __shfl_xor(ss, 4); ss += __shfl_xor(ss, 8);
;                     const float rs = rsqrtf(ss * (1.0f / 64.0f) + EPSV);
;                     bf16_t* rp = qk + (size_t)(pm * 256 + ai * 128 + wr * 64 + m * 16 + fq * 4 + j) * 2048 + head * 64 + fr;
; #pragma unroll
;                     for (int bj = 0; bj < 2; ++bj)
; #pragma unroll
;                         for (int n = 0; n < 2; ++n) rp[bj * 32 + n * 16] = (bf16_t)f2bf(acc[ai][bj][m][n][j] * rs * gv[bj][n]);
;                 }
	v_pk_add_f32 v[196:197], v[196:197], v[198:199]
	v_cvt_pk_bf16_f32 v161, v161, s0
	v_pk_fma_f32 v[196:197], v[196:197], s[8:9], v[162:163] op_sel_hi:[1,0,0]
	global_store_short v[194:195], v161, off offset:96
	v_mul_f32_e32 v161, 0x4b800000, v197
	v_cmp_gt_f32_e64 s[46:47], s93, v197
	v_mul_f32_e32 v192, v170, v192
	v_cvt_pk_bf16_f32 v192, v192, s0
	v_cndmask_b32_e64 v161, v197, v161, s[46:47]
	v_rsq_f32_e32 v161, v161
	global_store_short v[194:195], v192, off offset:64
	v_add_u32_e32 v194, 0xb0, v160
	v_ashrrev_i32_e32 v195, 31, v194
	v_mul_f32_e32 v192, 0x45800000, v161
	v_cndmask_b32_e64 v161, v161, v192, s[46:47]
	v_mul_f32_e32 v192, v78, v161
	v_lshlrev_b64 v[194:195], 12, v[194:195]
	v_mul_f32_e32 v192, v168, v192
	v_lshl_add_u64 v[194:195], v[158:159], 0, v[194:195]
	v_cvt_pk_bf16_f32 v192, v192, s0
	global_store_short v[194:195], v192, off
	v_mul_f32_e32 v192, v46, v161
	v_mul_f32_e32 v192, v169, v192
	v_cvt_pk_bf16_f32 v192, v192, s0
	global_store_short v[194:195], v192, off offset:32
	v_mul_f32_e32 v192, v18, v161
	v_mul_f32_e32 v161, v2, v161
	v_mul_f32_e32 v161, v171, v161
	v_cvt_pk_bf16_f32 v161, v161, s0
	v_cmp_gt_f32_e32 vcc, s93, v196
	global_store_short v[194:195], v161, off offset:96
	v_mul_f32_e32 v161, 0x4b800000, v196
	v_cndmask_b32_e32 v161, v196, v161, vcc
	v_rsq_f32_e32 v161, v161
	v_mul_f32_e32 v192, v170, v192
	v_cvt_pk_bf16_f32 v192, v192, s0
	global_store_short v[194:195], v192, off offset:64
	v_mul_f32_e32 v192, 0x45800000, v161
	v_cndmask_b32_e32 v161, v161, v192, vcc
	v_add_u32_e32 v194, 0xb1, v160
	v_ashrrev_i32_e32 v195, 31, v194
	v_mul_f32_e32 v192, v79, v161
	v_lshlrev_b64 v[194:195], 12, v[194:195]
	v_mul_f32_e32 v192, v168, v192
	v_lshl_add_u64 v[194:195], v[158:159], 0, v[194:195]
	v_cvt_pk_bf16_f32 v192, v192, s0
	global_store_short v[194:195], v192, off
	v_mul_f32_e32 v192, v47, v161
	v_mul_f32_e32 v192, v169, v192
	v_cvt_pk_bf16_f32 v192, v192, s0
	global_store_short v[194:195], v192, off offset:32
	v_mul_f32_e32 v192, v19, v161
	v_mul_f32_e32 v161, v3, v161
	v_mul_f32_e32 v192, v170, v192
	v_mul_f32_e32 v161, v171, v161
	v_cvt_pk_bf16_f32 v192, v192, s0
	v_cvt_pk_bf16_f32 v161, v161, s0
	global_store_short v[194:195], v192, off offset:64
	global_store_short v[194:195], v161, off offset:96
	v_mov_b32_e32 v194, v80
	v_mov_b32_e32 v195, v48
	v_mov_b32_e32 v200, v81
	v_mov_b32_e32 v201, v49
	v_pk_mul_f32 v[194:195], v[194:195], v[194:195]
	v_mov_b32_e32 v196, v20
	v_mov_b32_e32 v197, v4
	v_pk_mul_f32 v[200:201], v[200:201], v[200:201]
	v_mov_b32_e32 v203, v5
	v_pk_mul_f32 v[196:197], v[196:197], v[196:197]
	v_pk_mul_f32 v[202:203], v[202:203], v[202:203]
	v_mov_b32_e32 v204, v200
	v_mov_b32_e32 v205, v194
	v_mov_b32_e32 v194, v201
	v_pk_add_f32 v[194:195], v[204:205], v[194:195]
	v_mov_b32_e32 v200, v202
	v_mov_b32_e32 v201, v196
	v_pk_add_f32 v[194:195], v[194:195], v[200:201]
	v_mov_b32_e32 v196, v203
	v_pk_add_f32 v[194:195], v[194:195], v[196:197]
	ds_bpermute_b32 v197, v175, v195
	ds_bpermute_b32 v196, v175, v194
	v_add_u32_e32 v198, 0xb2, v160
	v_ashrrev_i32_e32 v199, 31, v198
	v_lshlrev_b64 v[198:199], 12, v[198:199]
	v_lshl_add_u64 v[198:199], v[158:159], 0, v[198:199]
	s_waitcnt lgkmcnt(0)
	v_pk_add_f32 v[194:195], v[194:195], v[196:197]
	ds_bpermute_b32 v175, v174, v195
	ds_bpermute_b32 v174, v174, v194
	v_add_u32_e32 v160, 0xb3, v160
	s_waitcnt lgkmcnt(0)
	v_pk_add_f32 v[174:175], v[194:195], v[174:175]
	ds_bpermute_b32 v195, v173, v175
	ds_bpermute_b32 v194, v173, v174
	s_waitcnt lgkmcnt(0)
	v_pk_add_f32 v[174:175], v[174:175], v[194:195]
	ds_bpermute_b32 v173, v172, v175
	ds_bpermute_b32 v172, v172, v174
	s_waitcnt lgkmcnt(0)
	v_pk_add_f32 v[172:173], v[174:175], v[172:173]
	s_nop 0
	v_pk_fma_f32 v[162:163], v[172:173], s[8:9], v[162:163] op_sel_hi:[1,0,0]
	s_nop 0
	v_mul_f32_e32 v161, 0x4b800000, v163
	v_cmp_gt_f32_e64 s[46:47], s93, v163
	v_cmp_gt_f32_e32 vcc, s93, v162
	s_nop 0
	v_cndmask_b32_e64 v161, v163, v161, s[46:47]
	v_rsq_f32_e32 v161, v161
	s_nop 0
	v_mul_f32_e32 v163, 0x45800000, v161
	v_cndmask_b32_e64 v161, v161, v163, s[46:47]
	v_mul_f32_e32 v163, v80, v161
	v_mul_f32_e32 v163, v168, v163
	v_cvt_pk_bf16_f32 v163, v163, s0
	global_store_short v[198:199], v163, off
	v_mul_f32_e32 v163, v48, v161
	v_mul_f32_e32 v163, v169, v163
	v_cvt_pk_bf16_f32 v163, v163, s0
	global_store_short v[198:199], v163, off offset:32
	v_mul_f32_e32 v163, v20, v161
	v_mul_f32_e32 v161, v4, v161
	v_mul_f32_e32 v161, v171, v161
	v_cvt_pk_bf16_f32 v161, v161, s0
	global_store_short v[198:199], v161, off offset:96
	v_mul_f32_e32 v161, 0x4b800000, v162
	v_cndmask_b32_e32 v161, v162, v161, vcc
	v_rsq_f32_e32 v161, v161
	v_mul_f32_e32 v163, v170, v163
	v_cvt_pk_bf16_f32 v163, v163, s0
	global_store_short v[198:199], v163, off offset:64
	v_mul_f32_e32 v162, 0x45800000, v161
	v_cndmask_b32_e32 v162, v161, v162, vcc
	v_ashrrev_i32_e32 v161, 31, v160
	v_lshlrev_b64 v[160:161], 12, v[160:161]
	v_lshl_add_u64 v[158:159], v[158:159], 0, v[160:161]
	v_mul_f32_e32 v160, v81, v162
	v_mul_f32_e32 v160, v168, v160
	v_cvt_pk_bf16_f32 v160, v160, s0
	global_store_short v[158:159], v160, off
	v_mul_f32_e32 v160, v49, v162
	v_mul_f32_e32 v160, v169, v160
	v_cvt_pk_bf16_f32 v160, v160, s0
	global_store_short v[158:159], v160, off offset:32
	v_mul_f32_e32 v160, v21, v162
	v_mul_f32_e32 v160, v170, v160
	v_cvt_pk_bf16_f32 v160, v160, s0
	global_store_short v[158:159], v160, off offset:64
	v_mul_f32_e32 v160, v5, v162
	v_mul_f32_e32 v160, v171, v160
	v_cvt_pk_bf16_f32 v160, v160, s0
	global_store_short v[158:159], v160, off offset:96

;     ...
;     for (int r = rbeg + gw; r < nrows; r += nw) {
;         const float* xp = (r < T_LAT) ? xlat + (size_t)r * DM : xctx + (size_t)(r - T_LAT) * DM;
;         const int m = (r < T_LAT) ? (r >> 12) : 8;
;         const float* mv = p.modv + ((size_t)layer * 9 + m) * 6144 + shift_i * 1024;
;         f32x4 v[4];
;         float ss = 0.f;
; #pragma unroll
;         for (int i = 0; i < 4; ++i) {
;             v[i] = *reinterpret_cast<const f32x4*>(xp + (i * 64 + lane) * 4);
;             ss += v[i][0] * v[i][0] + v[i][1] * v[i][1] + v[i][2] * v[i][2] + v[i][3] * v[i][3];
;         }
; #pragma unroll
;         for (int o = 32; o >= 1; o >>= 1) ss += __shfl_xor(ss, o);
;         const float rstd = rsqrtf(ss * (1.0f / 1024.0f) + EPSV);
;         bf16_t* hp = p.hbuf + (size_t)r * DM;
; #pragma unroll
;         for (int i = 0; i < 4; ++i) {
;             const int col = (i * 64 + lane) * 4;
;             f32x4 gg = *reinterpret_cast<const f32x4*>(g + col);
;             f32x4 sh = *reinterpret_cast<const f32x4*>(mv + col);
;             f32x4 sc = *reinterpret_cast<const f32x4*>(mv + 1024 + col);
;             float o0 = v[i][0] * rstd * gg[0] * (1.f + sc[0]) + sh[0];
;             float o1 = v[i][1] * rstd * gg[1] * (1.f + sc[1]) + sh[1];
;             float o2 = v[i][2] * rstd * gg[2] * (1.f + sc[2]) + sh[2];
;             float o3 = v[i][3] * rstd * gg[3] * (1.f + sc[3]) + sh[3];
;             u32x2 o = {pack2(o0, o1), pack2(o2, o3)};
;             *reinterpret_cast<u32x2*>(hp + col) = o;
;         }
;     }
.LBB0_1483:
	s_or_b64 exec, exec, s[14:15]
	v_mov_b32_e32 v29, v0
	v_lshl_add_u64 v[2:3], v[2:3], 0, v[28:29]
	global_load_dwordx4 v[14:17], v[2:3], off
	global_load_dwordx4 v[10:13], v[2:3], off offset:1024
	global_load_dwordx4 v[192:195], v[2:3], off offset:2048
	global_load_dwordx4 v[196:199], v[2:3], off offset:3072
	global_load_dwordx4 v[200:203], v[20:21], off
	global_load_dwordx4 v[204:207], v[20:21], off offset:1024
	global_load_dwordx4 v[208:211], v[20:21], off offset:2048
	global_load_dwordx4 v[212:215], v[20:21], off offset:3072
	v_min_i32_e32 v4, 0x8000, v4
	v_ashrrev_i32_e32 v4, 12, v4
	v_readlane_b32 s56, v254, 6
	v_ashrrev_i32_e32 v5, 31, v4
	v_readlane_b32 s62, v254, 12
	v_readlane_b32 s63, v254, 13
	v_lshl_add_u64 v[4:5], v[4:5], 0, s[20:21]
	s_movk_i32 s5, 0x6000
	v_mov_b64_e32 v[6:7], s[62:63]
	v_mad_u64_u32 v[40:41], s[0:1], v4, s5, v[6:7]
	v_mad_i32_i24 v41, v5, s5, v41
	v_lshlrev_b64 v[60:61], 11, v[42:43]
	v_lshl_add_u64 v[42:43], v[40:41], 0, s[22:23]
	v_lshl_add_u64 v[248:249], v[40:41], 0, s[18:19]
	v_mov_b32_e32 v33, v0
	v_mov_b32_e32 v35, v0
	v_mov_b32_e32 v242, v30
	v_mov_b32_e32 v243, v0
	v_lshl_add_u64 v[240:241], v[248:249], 0, v[28:29]
	global_load_dwordx4 v[52:55], v[240:241], off
	v_lshl_add_u64 v[240:241], v[42:43], 0, v[28:29]
	global_load_dwordx4 v[56:59], v[240:241], off
	v_lshl_add_u64 v[240:241], v[248:249], 0, v[242:243]
	global_load_dwordx4 v[216:219], v[240:241], off
	v_lshl_add_u64 v[240:241], v[42:43], 0, v[242:243]
	global_load_dwordx4 v[220:223], v[240:241], off
	v_lshl_add_u64 v[240:241], v[248:249], 0, v[32:33]
	global_load_dwordx4 v[224:227], v[240:241], off
	v_lshl_add_u64 v[240:241], v[42:43], 0, v[32:33]
	global_load_dwordx4 v[228:231], v[240:241], off
	v_lshl_add_u64 v[240:241], v[248:249], 0, v[34:35]
	global_load_dwordx4 v[232:235], v[240:241], off
	v_lshl_add_u64 v[240:241], v[42:43], 0, v[34:35]
	global_load_dwordx4 v[236:239], v[240:241], off
	v_add_u32_e32 v24, s38, v24
	v_lshl_add_u64 v[18:19], v[18:19], 0, s[38:39]
	v_lshl_add_u64 v[26:27], v[26:27], 0, s[16:17]
	v_readlane_b32 s57, v254, 7
	v_readlane_b32 s58, v254, 8
	v_readlane_b32 s59, v254, 9
	v_readlane_b32 s60, v254, 10
	s_waitcnt vmcnt(14)
	v_mov_b32_e32 v6, v15
	v_mov_b32_e32 v7, v11
	v_mov_b32_e32 v4, v14
	v_mov_b32_e32 v5, v10
	v_pk_mul_f32 v[6:7], v[6:7], v[6:7]
	v_readlane_b32 s61, v254, 11
	v_pk_fma_f32 v[4:5], v[4:5], v[4:5], v[6:7]
	v_mov_b32_e32 v6, v16
	v_mov_b32_e32 v7, v12
	v_pk_fma_f32 v[4:5], v[6:7], v[6:7], v[4:5]
	v_mov_b32_e32 v6, v17
	v_mov_b32_e32 v7, v13
	v_pk_fma_f32 v[38:39], v[6:7], v[6:7], v[4:5]
	s_waitcnt vmcnt(12)
	v_mov_b32_e32 v6, v192
	v_mov_b32_e32 v7, v193
	v_mov_b32_e32 v8, v194
	v_mov_b32_e32 v9, v195
	v_mov_b32_e32 v2, v196
	v_mov_b32_e32 v3, v197
	v_mov_b32_e32 v4, v198
	v_mov_b32_e32 v5, v199
	v_add_f32_e32 v25, v38, v39
	v_mov_b32_e32 v50, v7
	v_mov_b32_e32 v51, v3
	v_mov_b32_e32 v48, v6
	v_mov_b32_e32 v49, v2
	v_pk_mul_f32 v[50:51], v[50:51], v[50:51]
	s_waitcnt vmcnt(6)
	v_pk_add_f32 v[40:41], v[56:57], 1.0 op_sel_hi:[1,0]
	v_pk_fma_f32 v[48:49], v[48:49], v[48:49], v[50:51]
	v_mov_b32_e32 v50, v8
	v_mov_b32_e32 v51, v4
	v_pk_fma_f32 v[48:49], v[50:51], v[50:51], v[48:49]
	v_mov_b32_e32 v50, v9
	v_mov_b32_e32 v51, v5
	v_pk_fma_f32 v[48:49], v[50:51], v[50:51], v[48:49]
	s_nop 0
	v_add_f32_e32 v25, v25, v48
	v_add_f32_e32 v25, v25, v49
	ds_bpermute_b32 v31, v1, v25
	s_waitcnt lgkmcnt(0)
	v_add_f32_e32 v25, v25, v31
	ds_bpermute_b32 v31, v37, v25
	s_waitcnt lgkmcnt(0)
	v_add_f32_e32 v25, v25, v31
	ds_bpermute_b32 v31, v44, v25
	s_waitcnt lgkmcnt(0)
	v_add_f32_e32 v25, v25, v31
	ds_bpermute_b32 v31, v45, v25
	s_waitcnt lgkmcnt(0)
	v_add_f32_e32 v25, v25, v31
	ds_bpermute_b32 v31, v46, v25
	s_waitcnt lgkmcnt(0)
	v_add_f32_e32 v25, v25, v31
	ds_bpermute_b32 v31, v47, v25
	s_waitcnt lgkmcnt(0)
	v_add_f32_e32 v25, v25, v31
	v_fmamk_f32 v25, v25, 0x3a800000, v177
	v_cmp_gt_f32_e32 vcc, s93, v25
	v_mul_f32_e32 v31, 0x4b800000, v25
	s_nop 0
	v_cndmask_b32_e32 v25, v25, v31, vcc
	v_rsq_f32_e32 v25, v25
	s_nop 0
	v_mul_f32_e32 v31, 0x45800000, v25
	v_cndmask_b32_e32 v36, v25, v31, vcc
	v_pk_mul_f32 v[14:15], v[14:15], v[36:37] op_sel_hi:[1,0]
	v_pk_mul_f32 v[16:17], v[16:17], v[36:37] op_sel_hi:[1,0]
	v_mov_b32_e32 v31, v0
	v_pk_mul_f32 v[10:11], v[10:11], v[36:37] op_sel_hi:[1,0]
	v_pk_mul_f32 v[12:13], v[12:13], v[36:37] op_sel_hi:[1,0]
	v_pk_mul_f32 v[6:7], v[6:7], v[36:37] op_sel_hi:[1,0]
	v_pk_mul_f32 v[8:9], v[8:9], v[36:37] op_sel_hi:[1,0]
	v_pk_mul_f32 v[2:3], v[2:3], v[36:37] op_sel_hi:[1,0]
	v_pk_mul_f32 v[4:5], v[4:5], v[36:37] op_sel_hi:[1,0]
	s_waitcnt vmcnt(0)
	v_pk_mul_f32 v[14:15], v[200:201], v[14:15]
	s_nop 0
	v_pk_fma_f32 v[14:15], v[40:41], v[14:15], v[52:53]
	v_pk_mul_f32 v[16:17], v[202:203], v[16:17]
	v_pk_add_f32 v[40:41], v[58:59], 1.0 op_sel_hi:[1,0]
	v_cvt_pk_bf16_f32 v14, v14, v15
	v_pk_fma_f32 v[16:17], v[40:41], v[16:17], v[54:55]
	v_lshl_add_u64 v[40:41], v[22:23], 0, v[60:61]
	v_cvt_pk_bf16_f32 v15, v16, v17
	global_store_dwordx2 v[40:41], v[14:15], off
	v_pk_mul_f32 v[10:11], v[204:205], v[10:11]
	v_pk_mul_f32 v[12:13], v[206:207], v[12:13]
	v_pk_add_f32 v[14:15], v[220:221], 1.0 op_sel_hi:[1,0]
	s_nop 0
	v_pk_fma_f32 v[10:11], v[14:15], v[10:11], v[216:217]
	v_pk_add_f32 v[14:15], v[222:223], 1.0 op_sel_hi:[1,0]
	v_cvt_pk_bf16_f32 v10, v10, v11
	v_pk_fma_f32 v[12:13], v[14:15], v[12:13], v[218:219]
	v_pk_mul_f32 v[6:7], v[208:209], v[6:7]
	v_cvt_pk_bf16_f32 v11, v12, v13
	global_store_dwordx2 v[40:41], v[10:11], off offset:512
	v_pk_add_f32 v[10:11], v[228:229], 1.0 op_sel_hi:[1,0]
	v_pk_mul_f32 v[8:9], v[210:211], v[8:9]
	v_pk_fma_f32 v[6:7], v[10:11], v[6:7], v[224:225]
	v_pk_add_f32 v[10:11], v[230:231], 1.0 op_sel_hi:[1,0]
	v_cvt_pk_bf16_f32 v6, v6, v7
	v_pk_fma_f32 v[8:9], v[10:11], v[8:9], v[226:227]
	v_pk_mul_f32 v[2:3], v[2:3], v[212:213]
	v_cvt_pk_bf16_f32 v7, v8, v9
	global_store_dwordx2 v[40:41], v[6:7], off offset:1024
	v_pk_mul_f32 v[4:5], v[4:5], v[214:215]
	v_pk_add_f32 v[6:7], v[236:237], 1.0 op_sel_hi:[1,0]
	s_nop 0
	v_pk_fma_f32 v[2:3], v[2:3], v[6:7], v[232:233]
	v_pk_add_f32 v[6:7], v[238:239], 1.0 op_sel_hi:[1,0]
	v_cvt_pk_bf16_f32 v2, v2, v3
	v_pk_fma_f32 v[4:5], v[4:5], v[6:7], v[234:235]
	s_nop 0
	v_cvt_pk_bf16_f32 v3, v4, v5
	global_store_dwordx2 v[40:41], v[2:3], off offset:1536
	v_add_u32_e32 v2, 0x8000, v24
	v_cmp_lt_i32_e32 vcc, s94, v2
	s_or_b64 s[12:13], vcc, s[12:13]
	s_andn2_b64 exec, exec, s[12:13]
	s_cbranch_execz .LBB0_1486
